# v19: phase_fz LDS weight reads pipelined 5 pairs deep (same arithmetic order)
# speedup vs baseline: 1.0057x; 1.0040x over previous
.LBB0_641:
	s_or_b64 exec, exec, s[0:1]
	v_lshlrev_b32_e32 v104, 3, v106
	v_lshl_add_u32 v105, v107, 4, 0
	s_waitcnt vmcnt(7)
	ds_write_b128 v105, v[60:63]
	s_waitcnt vmcnt(6)
	ds_write_b128 v105, v[64:67] offset:8192
	s_waitcnt vmcnt(5)
	ds_write_b128 v105, v[68:71] offset:16384
	s_waitcnt vmcnt(4)
	ds_write_b128 v105, v[72:75] offset:24576
	s_waitcnt vmcnt(3)
	ds_write_b128 v105, v[76:79] offset:32768
	s_waitcnt vmcnt(2)
	ds_write_b128 v105, v[80:83] offset:40960
	s_waitcnt vmcnt(1)
	ds_write_b128 v105, v[88:91] offset:49152
	s_waitcnt vmcnt(0)
	ds_write_b128 v105, v[92:95] offset:57344
	v_mov_b32_e32 v62, v104
	s_waitcnt lgkmcnt(0)
	s_barrier
	v_and_b32_e32 v72, 0xffff0000, v84
	v_lshlrev_b32_e32 v62, 2, v62
	v_and_b32_e32 v194, -16, v62
	ds_read_b128 v[136:139], v194
	ds_read_b128 v[140:143], v194 offset:16
	ds_read_b128 v[144:147], v194 offset:8192
	ds_read_b128 v[148:151], v194 offset:8208
	ds_read_b128 v[152:155], v194 offset:16384
	ds_read_b128 v[156:159], v194 offset:16400
	ds_read_b128 v[160:163], v194 offset:24576
	ds_read_b128 v[164:167], v194 offset:24592
	ds_read_b128 v[196:199], v194 offset:32768
	ds_read_b128 v[200:203], v194 offset:32784
	v_lshlrev_b32_e32 v63, 16, v84
	v_lshlrev_b32_e32 v73, 16, v85
	v_and_b32_e32 v74, 0xffff0000, v85
	s_waitcnt lgkmcnt(9)
	v_mul_f32_e32 v79, v137, v72
	v_fmac_f32_e32 v79, v136, v63
	v_fmac_f32_e32 v79, v138, v73
	v_lshlrev_b32_e32 v75, 16, v86
	v_fmac_f32_e32 v79, v139, v74
	s_waitcnt lgkmcnt(8)
	v_fmac_f32_e32 v79, v140, v75
	ds_read_b128 v[204:207], v194 offset:40960
	ds_read_b128 v[208:211], v194 offset:40976
	v_and_b32_e32 v76, 0xffff0000, v86
	v_lshlrev_b32_e32 v77, 16, v87
	v_fmac_f32_e32 v79, v141, v76
	v_and_b32_e32 v78, 0xffff0000, v87
	v_fmac_f32_e32 v79, v142, v77
	v_fmac_f32_e32 v79, v143, v78
	s_waitcnt lgkmcnt(9)
	v_mul_f32_e32 v80, v145, v72
	v_fmac_f32_e32 v80, v144, v63
	v_fmac_f32_e32 v80, v146, v73
	v_fmac_f32_e32 v80, v147, v74
	s_waitcnt lgkmcnt(8)
	v_fmac_f32_e32 v80, v148, v75
	ds_read_b128 v[136:139], v194 offset:49152
	ds_read_b128 v[140:143], v194 offset:49168
	v_fmac_f32_e32 v80, v149, v76
	v_fmac_f32_e32 v80, v150, v77
	v_fmac_f32_e32 v80, v151, v78
	s_waitcnt lgkmcnt(9)
	v_mul_f32_e32 v81, v153, v72
	v_fmac_f32_e32 v81, v152, v63
	v_fmac_f32_e32 v81, v154, v73
	v_fmac_f32_e32 v81, v155, v74
	s_waitcnt lgkmcnt(8)
	v_fmac_f32_e32 v81, v156, v75
	ds_read_b128 v[144:147], v194 offset:57344
	ds_read_b128 v[148:151], v194 offset:57360
	v_fmac_f32_e32 v81, v157, v76
	v_fmac_f32_e32 v81, v158, v77
	v_fmac_f32_e32 v81, v159, v78
	s_waitcnt lgkmcnt(9)
	v_mul_f32_e32 v82, v161, v72
	v_fmac_f32_e32 v82, v160, v63
	v_fmac_f32_e32 v82, v162, v73
	v_fmac_f32_e32 v82, v163, v74
	s_waitcnt lgkmcnt(8)
	v_fmac_f32_e32 v82, v164, v75
	ds_read_b128 v[152:155], v194 offset:2048
	ds_read_b128 v[156:159], v194 offset:2064
	v_fmac_f32_e32 v82, v165, v76
	v_fmac_f32_e32 v82, v166, v77
	v_fmac_f32_e32 v82, v167, v78
	s_waitcnt lgkmcnt(9)
	v_mul_f32_e32 v83, v197, v72
	v_fmac_f32_e32 v83, v196, v63
	v_fmac_f32_e32 v83, v198, v73
	v_fmac_f32_e32 v83, v199, v74
	s_waitcnt lgkmcnt(8)
	v_fmac_f32_e32 v83, v200, v75
	ds_read_b128 v[160:163], v194 offset:10240
	ds_read_b128 v[164:167], v194 offset:10256
	v_fmac_f32_e32 v83, v201, v76
	v_fmac_f32_e32 v83, v202, v77
	v_fmac_f32_e32 v83, v203, v78
	s_waitcnt lgkmcnt(9)
	v_mul_f32_e32 v84, v205, v72
	v_fmac_f32_e32 v84, v204, v63
	v_fmac_f32_e32 v84, v206, v73
	v_fmac_f32_e32 v84, v207, v74
	s_waitcnt lgkmcnt(8)
	v_fmac_f32_e32 v84, v208, v75
	ds_read_b128 v[196:199], v194 offset:18432
	ds_read_b128 v[200:203], v194 offset:18448
	v_fmac_f32_e32 v84, v209, v76
	v_fmac_f32_e32 v84, v210, v77
	v_fmac_f32_e32 v84, v211, v78
	s_waitcnt lgkmcnt(9)
	v_mul_f32_e32 v85, v137, v72
	v_fmac_f32_e32 v85, v136, v63
	v_fmac_f32_e32 v85, v138, v73
	v_fmac_f32_e32 v85, v139, v74
	s_waitcnt lgkmcnt(8)
	v_fmac_f32_e32 v85, v140, v75
	ds_read_b128 v[204:207], v194 offset:26624
	ds_read_b128 v[208:211], v194 offset:26640
	v_fmac_f32_e32 v85, v141, v76
	v_fmac_f32_e32 v85, v142, v77
	v_fmac_f32_e32 v85, v143, v78
	s_waitcnt lgkmcnt(9)
	v_mul_f32_e32 v65, v145, v72
	v_fmac_f32_e32 v65, v144, v63
	v_fmac_f32_e32 v65, v146, v73
	v_fmac_f32_e32 v65, v147, v74
	s_waitcnt lgkmcnt(8)
	v_fmac_f32_e32 v65, v148, v75
	v_fmac_f32_e32 v65, v149, v76
	v_lshlrev_b32_e32 v68, 16, v56
	v_and_b32_e32 v69, 0xffff0000, v56
	v_fmac_f32_e32 v65, v150, v77
	v_fmac_f32_e32 v65, v151, v78
	v_add_f32_e32 v63, 0, v65
	ds_read_b128 v[136:139], v194 offset:34816
	ds_read_b128 v[140:143], v194 offset:34832
	v_lshlrev_b32_e32 v70, 16, v57
	v_and_b32_e32 v71, 0xffff0000, v57
	v_lshlrev_b32_e32 v72, 16, v58
	v_and_b32_e32 v73, 0xffff0000, v58
	v_lshlrev_b32_e32 v74, 16, v59
	v_and_b32_e32 v75, 0xffff0000, v59
	s_waitcnt lgkmcnt(9)
	v_mul_f32_e32 v76, v153, v69
	v_fmac_f32_e32 v76, v152, v68
	v_fmac_f32_e32 v76, v154, v70
	v_fmac_f32_e32 v76, v155, v71
	s_waitcnt lgkmcnt(8)
	v_fmac_f32_e32 v76, v156, v72
	ds_read_b128 v[144:147], v194 offset:43008
	ds_read_b128 v[148:151], v194 offset:43024
	v_fmac_f32_e32 v76, v157, v73
	v_fmac_f32_e32 v76, v158, v74
	v_fmac_f32_e32 v76, v159, v75
	s_waitcnt lgkmcnt(9)
	v_mul_f32_e32 v77, v161, v69
	v_fmac_f32_e32 v77, v160, v68
	v_fmac_f32_e32 v77, v162, v70
	v_fmac_f32_e32 v77, v163, v71
	s_waitcnt lgkmcnt(8)
	v_fmac_f32_e32 v77, v164, v72
	ds_read_b128 v[152:155], v194 offset:51200
	ds_read_b128 v[156:159], v194 offset:51216
	v_fmac_f32_e32 v77, v165, v73
	v_fmac_f32_e32 v77, v166, v74
	v_fmac_f32_e32 v77, v167, v75
	s_waitcnt lgkmcnt(9)
	v_mul_f32_e32 v78, v197, v69
	v_fmac_f32_e32 v78, v196, v68
	v_fmac_f32_e32 v78, v198, v70
	v_fmac_f32_e32 v78, v199, v71
	s_waitcnt lgkmcnt(8)
	v_fmac_f32_e32 v78, v200, v72
	ds_read_b128 v[160:163], v194 offset:59392
	ds_read_b128 v[164:167], v194 offset:59408
	v_fmac_f32_e32 v78, v201, v73
	v_fmac_f32_e32 v78, v202, v74
	v_add_f32_e32 v79, 0, v79
	v_fmac_f32_e32 v78, v203, v75
	v_add_f32_e32 v76, v79, v76
	s_waitcnt lgkmcnt(9)
	v_mul_f32_e32 v79, v205, v69
	v_fmac_f32_e32 v79, v204, v68
	v_fmac_f32_e32 v79, v206, v70
	v_fmac_f32_e32 v79, v207, v71
	s_waitcnt lgkmcnt(8)
	v_fmac_f32_e32 v79, v208, v72
	ds_read_b128 v[196:199], v194 offset:4096
	ds_read_b128 v[200:203], v194 offset:4112
	v_fmac_f32_e32 v79, v209, v73
	v_fmac_f32_e32 v79, v210, v74
	v_add_f32_e32 v80, 0, v80
	v_fmac_f32_e32 v79, v211, v75
	v_add_f32_e32 v77, v80, v77
	s_waitcnt lgkmcnt(9)
	v_mul_f32_e32 v80, v137, v69
	v_fmac_f32_e32 v80, v136, v68
	v_fmac_f32_e32 v80, v138, v70
	v_fmac_f32_e32 v80, v139, v71
	s_waitcnt lgkmcnt(8)
	v_fmac_f32_e32 v80, v140, v72
	ds_read_b128 v[204:207], v194 offset:12288
	ds_read_b128 v[208:211], v194 offset:12304
	v_fmac_f32_e32 v80, v141, v73
	v_fmac_f32_e32 v80, v142, v74
	v_add_f32_e32 v81, 0, v81
	v_fmac_f32_e32 v80, v143, v75
	v_add_f32_e32 v78, v81, v78
	s_waitcnt lgkmcnt(9)
	v_mul_f32_e32 v81, v145, v69
	v_fmac_f32_e32 v81, v144, v68
	v_fmac_f32_e32 v81, v146, v70
	v_fmac_f32_e32 v81, v147, v71
	s_waitcnt lgkmcnt(8)
	v_fmac_f32_e32 v81, v148, v72
	ds_read_b128 v[136:139], v194 offset:20480
	ds_read_b128 v[140:143], v194 offset:20496
	v_fmac_f32_e32 v81, v149, v73
	v_fmac_f32_e32 v81, v150, v74
	v_add_f32_e32 v82, 0, v82
	v_fmac_f32_e32 v81, v151, v75
	v_add_f32_e32 v79, v82, v79
	s_waitcnt lgkmcnt(9)
	v_mul_f32_e32 v82, v153, v69
	v_fmac_f32_e32 v82, v152, v68
	v_fmac_f32_e32 v82, v154, v70
	v_fmac_f32_e32 v82, v155, v71
	s_waitcnt lgkmcnt(8)
	v_fmac_f32_e32 v82, v156, v72
	ds_read_b128 v[144:147], v194 offset:28672
	ds_read_b128 v[148:151], v194 offset:28688
	v_fmac_f32_e32 v82, v157, v73
	v_fmac_f32_e32 v82, v158, v74
	v_fmac_f32_e32 v82, v159, v75
	s_waitcnt lgkmcnt(9)
	v_mul_f32_e32 v65, v161, v69
	v_fmac_f32_e32 v65, v160, v68
	v_fmac_f32_e32 v65, v162, v70
	v_fmac_f32_e32 v65, v163, v71
	s_waitcnt lgkmcnt(8)
	v_fmac_f32_e32 v65, v164, v72
	v_fmac_f32_e32 v65, v165, v73
	v_fmac_f32_e32 v65, v166, v74
	v_fmac_f32_e32 v65, v167, v75
	v_add_f32_e32 v63, v63, v65
	v_lshlrev_b32_e32 v64, 16, v52
	v_and_b32_e32 v65, 0xffff0000, v52
	ds_read_b128 v[152:155], v194 offset:36864
	ds_read_b128 v[156:159], v194 offset:36880
	v_lshlrev_b32_e32 v66, 16, v53
	v_and_b32_e32 v67, 0xffff0000, v53
	v_lshlrev_b32_e32 v68, 16, v54
	v_and_b32_e32 v69, 0xffff0000, v54
	v_lshlrev_b32_e32 v70, 16, v55
	v_and_b32_e32 v71, 0xffff0000, v55
	s_waitcnt lgkmcnt(9)
	v_mul_f32_e32 v72, v197, v65
	v_fmac_f32_e32 v72, v196, v64
	v_fmac_f32_e32 v72, v198, v66
	v_fmac_f32_e32 v72, v199, v67
	s_waitcnt lgkmcnt(8)
	v_fmac_f32_e32 v72, v200, v68
	ds_read_b128 v[160:163], v194 offset:45056
	ds_read_b128 v[164:167], v194 offset:45072
	v_fmac_f32_e32 v72, v201, v69
	v_fmac_f32_e32 v72, v202, v70
	v_fmac_f32_e32 v72, v203, v71
	s_waitcnt lgkmcnt(9)
	v_mul_f32_e32 v73, v205, v65
	v_fmac_f32_e32 v73, v204, v64
	v_fmac_f32_e32 v73, v206, v66
	v_fmac_f32_e32 v73, v207, v67
	s_waitcnt lgkmcnt(8)
	v_fmac_f32_e32 v73, v208, v68
	ds_read_b128 v[196:199], v194 offset:53248
	ds_read_b128 v[200:203], v194 offset:53264
	v_fmac_f32_e32 v73, v209, v69
	v_fmac_f32_e32 v73, v210, v70
	v_fmac_f32_e32 v73, v211, v71
	s_waitcnt lgkmcnt(9)
	v_mul_f32_e32 v74, v137, v65
	v_fmac_f32_e32 v74, v136, v64
	v_fmac_f32_e32 v74, v138, v66
	v_fmac_f32_e32 v74, v139, v67
	s_waitcnt lgkmcnt(8)
	v_fmac_f32_e32 v74, v140, v68
	ds_read_b128 v[204:207], v194 offset:61440
	ds_read_b128 v[208:211], v194 offset:61456
	v_fmac_f32_e32 v74, v141, v69
	v_fmac_f32_e32 v74, v142, v70
	v_fmac_f32_e32 v74, v143, v71
	s_waitcnt lgkmcnt(9)
	v_mul_f32_e32 v75, v145, v65
	v_fmac_f32_e32 v75, v144, v64
	v_fmac_f32_e32 v75, v146, v66
	v_fmac_f32_e32 v75, v147, v67
	s_waitcnt lgkmcnt(8)
	v_fmac_f32_e32 v75, v148, v68
	ds_read_b128 v[136:139], v194 offset:6144
	ds_read_b128 v[140:143], v194 offset:6160
	v_fmac_f32_e32 v75, v149, v69
	v_fmac_f32_e32 v75, v150, v70
	v_fmac_f32_e32 v75, v151, v71
	v_add_f32_e32 v72, v76, v72
	s_waitcnt lgkmcnt(9)
	v_mul_f32_e32 v76, v153, v65
	v_fmac_f32_e32 v76, v152, v64
	v_fmac_f32_e32 v76, v154, v66
	v_fmac_f32_e32 v76, v155, v67
	s_waitcnt lgkmcnt(8)
	v_fmac_f32_e32 v76, v156, v68
	ds_read_b128 v[144:147], v194 offset:14336
	ds_read_b128 v[148:151], v194 offset:14352
	v_fmac_f32_e32 v76, v157, v69
	v_fmac_f32_e32 v76, v158, v70
	v_fmac_f32_e32 v76, v159, v71
	v_add_f32_e32 v73, v77, v73
	s_waitcnt lgkmcnt(9)
	v_mul_f32_e32 v77, v161, v65
	v_fmac_f32_e32 v77, v160, v64
	v_fmac_f32_e32 v77, v162, v66
	v_fmac_f32_e32 v77, v163, v67
	s_waitcnt lgkmcnt(8)
	v_fmac_f32_e32 v77, v164, v68
	ds_read_b128 v[152:155], v194 offset:22528
	ds_read_b128 v[156:159], v194 offset:22544
	v_fmac_f32_e32 v77, v165, v69
	v_fmac_f32_e32 v77, v166, v70
	v_fmac_f32_e32 v77, v167, v71
	v_add_f32_e32 v74, v78, v74
	s_waitcnt lgkmcnt(9)
	v_mul_f32_e32 v78, v197, v65
	v_fmac_f32_e32 v78, v196, v64
	v_fmac_f32_e32 v78, v198, v66
	v_fmac_f32_e32 v78, v199, v67
	s_waitcnt lgkmcnt(8)
	v_fmac_f32_e32 v78, v200, v68
	ds_read_b128 v[160:163], v194 offset:30720
	ds_read_b128 v[164:167], v194 offset:30736
	v_fmac_f32_e32 v78, v201, v69
	v_fmac_f32_e32 v78, v202, v70
	v_fmac_f32_e32 v78, v203, v71
	s_waitcnt lgkmcnt(9)
	v_mul_f32_e32 v57, v205, v65
	v_fmac_f32_e32 v57, v204, v64
	v_fmac_f32_e32 v57, v206, v66
	v_fmac_f32_e32 v57, v207, v67
	s_waitcnt lgkmcnt(8)
	v_fmac_f32_e32 v57, v208, v68
	v_fmac_f32_e32 v57, v209, v69
	v_fmac_f32_e32 v57, v210, v70
	v_fmac_f32_e32 v57, v211, v71
	v_add_f32_e32 v56, v63, v57
	v_lshlrev_b32_e32 v57, 16, v48
	v_and_b32_e32 v58, 0xffff0000, v48
	ds_read_b128 v[196:199], v194 offset:38912
	ds_read_b128 v[200:203], v194 offset:38928
	v_lshlrev_b32_e32 v59, 16, v49
	v_and_b32_e32 v63, 0xffff0000, v49
	v_lshlrev_b32_e32 v64, 16, v50
	v_and_b32_e32 v65, 0xffff0000, v50
	v_lshlrev_b32_e32 v66, 16, v51
	v_and_b32_e32 v67, 0xffff0000, v51
	s_waitcnt lgkmcnt(9)
	v_mul_f32_e32 v68, v137, v58
	v_fmac_f32_e32 v68, v136, v57
	v_fmac_f32_e32 v68, v138, v59
	v_fmac_f32_e32 v68, v139, v63
	s_waitcnt lgkmcnt(8)
	v_fmac_f32_e32 v68, v140, v64
	ds_read_b128 v[204:207], v194 offset:47104
	ds_read_b128 v[208:211], v194 offset:47120
	v_fmac_f32_e32 v68, v141, v65
	v_fmac_f32_e32 v68, v142, v66
	v_fmac_f32_e32 v68, v143, v67
	s_waitcnt lgkmcnt(9)
	v_mul_f32_e32 v69, v145, v58
	v_fmac_f32_e32 v69, v144, v57
	v_fmac_f32_e32 v69, v146, v59
	v_fmac_f32_e32 v69, v147, v63
	s_waitcnt lgkmcnt(8)
	v_fmac_f32_e32 v69, v148, v64
	ds_read_b128 v[136:139], v194 offset:55296
	ds_read_b128 v[140:143], v194 offset:55312
	v_fmac_f32_e32 v69, v149, v65
	v_fmac_f32_e32 v69, v150, v66
	v_fmac_f32_e32 v69, v151, v67
	s_waitcnt lgkmcnt(9)
	v_mul_f32_e32 v70, v153, v58
	v_fmac_f32_e32 v70, v152, v57
	v_fmac_f32_e32 v70, v154, v59
	v_fmac_f32_e32 v70, v155, v63
	s_waitcnt lgkmcnt(8)
	v_fmac_f32_e32 v70, v156, v64
	ds_read_b128 v[144:147], v194 offset:63488
	ds_read_b128 v[148:151], v194 offset:63504
	v_fmac_f32_e32 v70, v157, v65
	v_fmac_f32_e32 v70, v158, v66
	v_fmac_f32_e32 v70, v159, v67
	s_waitcnt lgkmcnt(9)
	v_mul_f32_e32 v71, v161, v58
	v_fmac_f32_e32 v71, v160, v57
	v_fmac_f32_e32 v71, v162, v59
	v_fmac_f32_e32 v71, v163, v63
	s_waitcnt lgkmcnt(8)
	v_fmac_f32_e32 v71, v164, v64
	v_fmac_f32_e32 v71, v165, v65
	v_fmac_f32_e32 v71, v166, v66
	v_fmac_f32_e32 v71, v167, v67
	v_add_f32_e32 v68, v72, v68
	s_waitcnt lgkmcnt(7)
	v_mul_f32_e32 v72, v197, v58
	v_fmac_f32_e32 v72, v196, v57
	v_fmac_f32_e32 v72, v198, v59
	v_fmac_f32_e32 v72, v199, v63
	s_waitcnt lgkmcnt(6)
	v_fmac_f32_e32 v72, v200, v64
	v_fmac_f32_e32 v72, v201, v65
	v_fmac_f32_e32 v72, v202, v66
	v_fmac_f32_e32 v72, v203, v67
	v_add_f32_e32 v69, v73, v69
	s_waitcnt lgkmcnt(5)
	v_mul_f32_e32 v73, v205, v58
	v_fmac_f32_e32 v73, v204, v57
	v_fmac_f32_e32 v73, v206, v59
	v_fmac_f32_e32 v73, v207, v63
	s_waitcnt lgkmcnt(4)
	v_fmac_f32_e32 v73, v208, v64
	v_fmac_f32_e32 v73, v209, v65
	v_fmac_f32_e32 v73, v210, v66
	v_fmac_f32_e32 v73, v211, v67
	v_add_f32_e32 v70, v74, v70
	s_waitcnt lgkmcnt(3)
	v_mul_f32_e32 v74, v137, v58
	v_fmac_f32_e32 v74, v136, v57
	v_fmac_f32_e32 v74, v138, v59
	v_fmac_f32_e32 v74, v139, v63
	s_waitcnt lgkmcnt(2)
	v_fmac_f32_e32 v74, v140, v64
	v_fmac_f32_e32 v74, v141, v65
	v_fmac_f32_e32 v74, v142, v66
	v_fmac_f32_e32 v74, v143, v67
	s_waitcnt lgkmcnt(1)
	v_mul_f32_e32 v53, v145, v58
	v_fmac_f32_e32 v53, v144, v57
	v_fmac_f32_e32 v53, v146, v59
	v_fmac_f32_e32 v53, v147, v63
	s_waitcnt lgkmcnt(0)
	v_fmac_f32_e32 v53, v148, v64
	v_lshlrev_b32_e32 v128, 2, v106
	v_fmac_f32_e32 v53, v149, v65
	v_fmac_f32_e32 v53, v150, v66
	v_xor_b32_e32 v50, 4, v128
	v_fmac_f32_e32 v53, v151, v67
	ds_bpermute_b32 v48, v50, v68
	ds_bpermute_b32 v51, v50, v69
	v_add_f32_e32 v83, 0, v83
	v_add_f32_e32 v84, 0, v84
	v_add_f32_e32 v85, 0, v85
	v_add_f32_e32 v80, v83, v80
	v_add_f32_e32 v81, v84, v81
	v_add_f32_e32 v82, v85, v82
	v_add_f32_e32 v75, v79, v75
	v_add_f32_e32 v76, v80, v76
	v_add_f32_e32 v77, v81, v77
	v_add_f32_e32 v78, v82, v78
	v_add_f32_e32 v71, v75, v71
	v_add_f32_e32 v72, v76, v72
	v_add_f32_e32 v73, v77, v73
	v_add_f32_e32 v49, v56, v53
	ds_bpermute_b32 v52, v50, v70
	s_waitcnt lgkmcnt(2)
	v_add_f32_e32 v55, v68, v48
	s_waitcnt lgkmcnt(1)
	v_add_f32_e32 v51, v69, v51
	v_xor_b32_e32 v48, 8, v128
	v_add_f32_e32 v62, v78, v74
	ds_bpermute_b32 v53, v50, v71
	ds_bpermute_b32 v54, v50, v72
	ds_bpermute_b32 v56, v50, v73
	ds_bpermute_b32 v58, v50, v49
	ds_bpermute_b32 v63, v48, v51
	ds_bpermute_b32 v57, v50, v62
	ds_bpermute_b32 v59, v48, v55
	s_waitcnt lgkmcnt(7)
	v_add_f32_e32 v52, v70, v52
	s_waitcnt lgkmcnt(6)
	v_add_f32_e32 v53, v71, v53
	s_waitcnt lgkmcnt(5)
	v_add_f32_e32 v54, v72, v54
	s_waitcnt lgkmcnt(4)
	v_add_f32_e32 v56, v73, v56
	s_waitcnt lgkmcnt(3)
	v_add_f32_e32 v49, v49, v58
	s_waitcnt lgkmcnt(2)
	v_add_f32_e32 v58, v51, v63
	ds_bpermute_b32 v51, v48, v52
	s_waitcnt lgkmcnt(2)
	v_add_f32_e32 v57, v62, v57
	s_waitcnt lgkmcnt(1)
	v_add_f32_e32 v55, v55, v59
	ds_bpermute_b32 v59, v48, v53
	ds_bpermute_b32 v62, v48, v54
	ds_bpermute_b32 v63, v48, v56
	ds_bpermute_b32 v64, v48, v57
	s_waitcnt lgkmcnt(4)
	v_add_f32_e32 v52, v52, v51
	v_xor_b32_e32 v51, 16, v128
	s_waitcnt lgkmcnt(3)
	v_add_f32_e32 v53, v53, v59
	s_waitcnt lgkmcnt(2)
	v_add_f32_e32 v54, v54, v62
	s_waitcnt lgkmcnt(1)
	v_add_f32_e32 v56, v56, v63
	ds_bpermute_b32 v59, v48, v49
	ds_bpermute_b32 v62, v51, v55
	ds_bpermute_b32 v63, v51, v58
	s_waitcnt lgkmcnt(3)
	v_add_f32_e32 v57, v57, v64
	ds_bpermute_b32 v64, v51, v52
	ds_bpermute_b32 v65, v51, v53
	s_waitcnt lgkmcnt(4)
	v_add_f32_e32 v59, v49, v59
	s_waitcnt lgkmcnt(3)
	v_add_f32_e32 v55, v55, v62
	s_waitcnt lgkmcnt(2)
	v_add_f32_e32 v58, v58, v63
	ds_bpermute_b32 v62, v51, v54
	ds_bpermute_b32 v63, v51, v56
	v_xor_b32_e32 v49, 32, v128
	s_waitcnt lgkmcnt(3)
	v_add_f32_e32 v52, v52, v64
	s_waitcnt lgkmcnt(2)
	v_add_f32_e32 v53, v53, v65
	ds_bpermute_b32 v64, v51, v57
	ds_bpermute_b32 v65, v51, v59
	ds_bpermute_b32 v66, v49, v55
	s_waitcnt lgkmcnt(4)
	v_add_f32_e32 v54, v54, v62
	s_waitcnt lgkmcnt(3)
	v_add_f32_e32 v56, v56, v63
	s_waitcnt lgkmcnt(2)
	v_add_f32_e32 v57, v57, v64
	s_waitcnt lgkmcnt(1)
	v_add_f32_e32 v59, v59, v65
	s_waitcnt lgkmcnt(0)
	v_add_f32_e32 v55, v55, v66
	ds_bpermute_b32 v62, v49, v58
	ds_bpermute_b32 v63, v49, v52
	ds_bpermute_b32 v64, v49, v53
	ds_bpermute_b32 v65, v49, v54
	ds_bpermute_b32 v66, v49, v56
	s_waitcnt lgkmcnt(4)
	v_add_f32_e32 v58, v58, v62
	s_waitcnt lgkmcnt(3)
	v_add_f32_e32 v62, v52, v63
	s_waitcnt lgkmcnt(2)
	v_add_f32_e32 v53, v53, v64
	s_waitcnt lgkmcnt(1)
	v_add_f32_e32 v63, v54, v65
	s_waitcnt lgkmcnt(0)
	v_add_f32_e32 v64, v56, v66
	ds_bpermute_b32 v54, v49, v57
	ds_bpermute_b32 v56, v49, v59
	v_xor_b32_e32 v52, 64, v128
	ds_bpermute_b32 v65, v52, v55
	ds_bpermute_b32 v66, v52, v58
	ds_bpermute_b32 v67, v52, v62
	s_waitcnt lgkmcnt(4)
	v_add_f32_e32 v68, v57, v54
	s_waitcnt lgkmcnt(3)
	v_add_f32_e32 v59, v59, v56
	s_waitcnt lgkmcnt(2)
	v_add_f32_e32 v54, v55, v65
	s_waitcnt lgkmcnt(1)
	v_add_f32_e32 v55, v58, v66
	s_waitcnt lgkmcnt(0)
	v_add_f32_e32 v56, v62, v67
	ds_bpermute_b32 v57, v52, v53
	ds_bpermute_b32 v58, v52, v63
	ds_bpermute_b32 v62, v52, v64
	ds_bpermute_b32 v65, v52, v68
	ds_bpermute_b32 v66, v52, v59
	s_waitcnt lgkmcnt(4)
	v_add_f32_e32 v57, v53, v57
	s_waitcnt lgkmcnt(3)
	v_add_f32_e32 v58, v63, v58
	s_waitcnt lgkmcnt(2)
	v_add_f32_e32 v62, v64, v62
	s_waitcnt lgkmcnt(1)
	v_add_f32_e32 v64, v68, v65
	s_waitcnt lgkmcnt(0)
	v_add_f32_e32 v66, v59, v66
	v_xor_b32_e32 v53, 0x80, v128
	ds_bpermute_b32 v59, v53, v54
	ds_bpermute_b32 v63, v53, v55
	ds_bpermute_b32 v65, v53, v56
	ds_bpermute_b32 v67, v53, v57
	ds_bpermute_b32 v68, v53, v58
	ds_bpermute_b32 v69, v53, v62
	ds_bpermute_b32 v70, v53, v64
	ds_bpermute_b32 v71, v53, v66
	v_readlane_b32 s0, v253, 29
	v_cmp_gt_u32_e64 s[38:39], 8, v106
	v_readlane_b32 s1, v253, 30
	v_cmp_eq_u32_e64 s[42:43], 1, v106
	v_cmp_eq_u32_e64 s[44:45], 2, v106
	v_lshl_add_u64 v[60:61], s[0:1], 0, v[128:129]
	v_cmp_eq_u32_e64 s[46:47], 3, v106
	v_cmp_eq_u32_e64 s[48:49], 4, v106
	v_cmp_eq_u32_e64 s[50:51], 5, v106
	v_cmp_eq_u32_e64 s[52:53], 6, v106
	v_cmp_eq_u32_e64 s[54:55], 7, v106
	s_and_b64 s[4:5], s[38:39], s[58:59]
	s_and_saveexec_b64 s[0:1], s[4:5]
	s_cbranch_execz .LBB0_643
	s_waitcnt lgkmcnt(6)
	v_add_f32_e32 v55, v55, v63
	v_add_f32_e32 v54, v54, v59
	s_waitcnt lgkmcnt(5)
	v_add_f32_e32 v56, v56, v65
	v_cndmask_b32_e64 v54, v54, v55, s[42:43]
	s_waitcnt lgkmcnt(4)
	v_add_f32_e32 v57, v57, v67
	v_cndmask_b32_e64 v54, v54, v56, s[44:45]
	s_waitcnt lgkmcnt(3)
	v_add_f32_e32 v58, v58, v68
	v_cndmask_b32_e64 v54, v54, v57, s[46:47]
	s_waitcnt lgkmcnt(2)
	v_add_f32_e32 v62, v62, v69
	v_cndmask_b32_e64 v54, v54, v58, s[48:49]
	s_waitcnt lgkmcnt(1)
	v_add_f32_e32 v64, v64, v70
	v_cndmask_b32_e64 v54, v54, v62, s[50:51]
	s_waitcnt lgkmcnt(0)
	v_add_f32_e32 v66, v66, v71
	v_cndmask_b32_e64 v54, v54, v64, s[52:53]
	v_cndmask_b32_e64 v56, v54, v66, s[54:55]
	v_lshlrev_b64 v[54:55], 5, v[102:103]
	v_lshl_add_u64 v[54:55], v[60:61], 0, v[54:55]
	global_store_dword v[54:55], v56, off
.LBB0_643:
	s_or_b64 exec, exec, s[0:1]
	v_mov_b32_e32 v54, v104
	v_lshlrev_b32_e32 v58, 16, v44
	s_waitcnt lgkmcnt(7)
	v_and_b32_e32 v59, 0xffff0000, v44
	v_lshlrev_b32_e32 v44, 2, v54
	v_and_b32_e32 v194, -16, v44
	ds_read_b128 v[136:139], v194
	ds_read_b128 v[140:143], v194 offset:16
	ds_read_b128 v[144:147], v194 offset:8192
	ds_read_b128 v[148:151], v194 offset:8208
	ds_read_b128 v[152:155], v194 offset:16384
	ds_read_b128 v[156:159], v194 offset:16400
	ds_read_b128 v[160:163], v194 offset:24576
	ds_read_b128 v[164:167], v194 offset:24592
	ds_read_b128 v[196:199], v194 offset:32768
	ds_read_b128 v[200:203], v194 offset:32784
	v_lshlrev_b32_e32 v66, 16, v45
	v_and_b32_e32 v45, 0xffff0000, v45
	v_lshlrev_b32_e32 v67, 16, v46
	s_waitcnt lgkmcnt(9)
	v_mul_f32_e32 v69, v137, v59
	v_fmac_f32_e32 v69, v136, v58
	v_fmac_f32_e32 v69, v138, v66
	v_fmac_f32_e32 v69, v139, v45
	s_waitcnt lgkmcnt(8)
	v_fmac_f32_e32 v69, v140, v67
	ds_read_b128 v[204:207], v194 offset:40960
	ds_read_b128 v[208:211], v194 offset:40976
	v_and_b32_e32 v46, 0xffff0000, v46
	v_lshlrev_b32_e32 v68, 16, v47
	v_fmac_f32_e32 v69, v141, v46
	v_and_b32_e32 v47, 0xffff0000, v47
	v_fmac_f32_e32 v69, v142, v68
	v_fmac_f32_e32 v69, v143, v47
	s_waitcnt lgkmcnt(9)
	v_mul_f32_e32 v70, v145, v59
	v_fmac_f32_e32 v70, v144, v58
	v_fmac_f32_e32 v70, v146, v66
	v_fmac_f32_e32 v70, v147, v45
	s_waitcnt lgkmcnt(8)
	v_fmac_f32_e32 v70, v148, v67
	ds_read_b128 v[136:139], v194 offset:49152
	ds_read_b128 v[140:143], v194 offset:49168
	v_fmac_f32_e32 v70, v149, v46
	v_fmac_f32_e32 v70, v150, v68
	v_fmac_f32_e32 v70, v151, v47
	s_waitcnt lgkmcnt(9)
	v_mul_f32_e32 v71, v153, v59
	v_fmac_f32_e32 v71, v152, v58
	v_fmac_f32_e32 v71, v154, v66
	v_fmac_f32_e32 v71, v155, v45
	s_waitcnt lgkmcnt(8)
	v_fmac_f32_e32 v71, v156, v67
	ds_read_b128 v[144:147], v194 offset:57344
	ds_read_b128 v[148:151], v194 offset:57360
	v_fmac_f32_e32 v71, v157, v46
	v_fmac_f32_e32 v71, v158, v68
	v_fmac_f32_e32 v71, v159, v47
	s_waitcnt lgkmcnt(9)
	v_mul_f32_e32 v72, v161, v59
	v_fmac_f32_e32 v72, v160, v58
	v_fmac_f32_e32 v72, v162, v66
	v_fmac_f32_e32 v72, v163, v45
	s_waitcnt lgkmcnt(8)
	v_fmac_f32_e32 v72, v164, v67
	ds_read_b128 v[152:155], v194 offset:2048
	ds_read_b128 v[156:159], v194 offset:2064
	v_fmac_f32_e32 v72, v165, v46
	v_fmac_f32_e32 v72, v166, v68
	v_fmac_f32_e32 v72, v167, v47
	s_waitcnt lgkmcnt(9)
	v_mul_f32_e32 v73, v197, v59
	v_fmac_f32_e32 v73, v196, v58
	v_fmac_f32_e32 v73, v198, v66
	v_fmac_f32_e32 v73, v199, v45
	s_waitcnt lgkmcnt(8)
	v_fmac_f32_e32 v73, v200, v67
	ds_read_b128 v[160:163], v194 offset:10240
	ds_read_b128 v[164:167], v194 offset:10256
	v_fmac_f32_e32 v73, v201, v46
	v_fmac_f32_e32 v73, v202, v68
	v_fmac_f32_e32 v73, v203, v47
	s_waitcnt lgkmcnt(9)
	v_mul_f32_e32 v74, v205, v59
	v_fmac_f32_e32 v74, v204, v58
	v_fmac_f32_e32 v74, v206, v66
	v_fmac_f32_e32 v74, v207, v45
	s_waitcnt lgkmcnt(8)
	v_fmac_f32_e32 v74, v208, v67
	ds_read_b128 v[196:199], v194 offset:18432
	ds_read_b128 v[200:203], v194 offset:18448
	v_fmac_f32_e32 v74, v209, v46
	v_fmac_f32_e32 v74, v210, v68
	v_fmac_f32_e32 v74, v211, v47
	s_waitcnt lgkmcnt(9)
	v_mul_f32_e32 v75, v137, v59
	v_fmac_f32_e32 v75, v136, v58
	v_fmac_f32_e32 v75, v138, v66
	v_fmac_f32_e32 v75, v139, v45
	s_waitcnt lgkmcnt(8)
	v_fmac_f32_e32 v75, v140, v67
	ds_read_b128 v[204:207], v194 offset:26624
	ds_read_b128 v[208:211], v194 offset:26640
	v_fmac_f32_e32 v75, v141, v46
	v_fmac_f32_e32 v75, v142, v68
	v_fmac_f32_e32 v75, v143, v47
	s_waitcnt lgkmcnt(9)
	v_mul_f32_e32 v55, v145, v59
	v_fmac_f32_e32 v55, v144, v58
	v_fmac_f32_e32 v55, v146, v66
	v_fmac_f32_e32 v55, v147, v45
	s_waitcnt lgkmcnt(8)
	v_fmac_f32_e32 v55, v148, v67
	v_fmac_f32_e32 v55, v149, v46
	v_fmac_f32_e32 v55, v150, v68
	v_fmac_f32_e32 v55, v151, v47
	v_lshlrev_b32_e32 v46, 16, v40
	v_and_b32_e32 v47, 0xffff0000, v40
	v_add_f32_e32 v45, 0, v55
	ds_read_b128 v[136:139], v194 offset:34816
	ds_read_b128 v[140:143], v194 offset:34832
	v_lshlrev_b32_e32 v58, 16, v41
	v_and_b32_e32 v59, 0xffff0000, v41
	v_lshlrev_b32_e32 v62, 16, v42
	v_and_b32_e32 v63, 0xffff0000, v42
	v_lshlrev_b32_e32 v64, 16, v43
	v_and_b32_e32 v65, 0xffff0000, v43
	s_waitcnt lgkmcnt(9)
	v_mul_f32_e32 v66, v153, v47
	v_fmac_f32_e32 v66, v152, v46
	v_fmac_f32_e32 v66, v154, v58
	v_fmac_f32_e32 v66, v155, v59
	s_waitcnt lgkmcnt(8)
	v_fmac_f32_e32 v66, v156, v62
	ds_read_b128 v[144:147], v194 offset:43008
	ds_read_b128 v[148:151], v194 offset:43024
	v_fmac_f32_e32 v66, v157, v63
	v_fmac_f32_e32 v66, v158, v64
	v_fmac_f32_e32 v66, v159, v65
	s_waitcnt lgkmcnt(9)
	v_mul_f32_e32 v67, v161, v47
	v_fmac_f32_e32 v67, v160, v46
	v_fmac_f32_e32 v67, v162, v58
	v_fmac_f32_e32 v67, v163, v59
	s_waitcnt lgkmcnt(8)
	v_fmac_f32_e32 v67, v164, v62
	ds_read_b128 v[152:155], v194 offset:51200
	ds_read_b128 v[156:159], v194 offset:51216
	v_fmac_f32_e32 v67, v165, v63
	v_fmac_f32_e32 v67, v166, v64
	v_fmac_f32_e32 v67, v167, v65
	s_waitcnt lgkmcnt(9)
	v_mul_f32_e32 v68, v197, v47
	v_fmac_f32_e32 v68, v196, v46
	v_fmac_f32_e32 v68, v198, v58
	v_fmac_f32_e32 v68, v199, v59
	s_waitcnt lgkmcnt(8)
	v_fmac_f32_e32 v68, v200, v62
	ds_read_b128 v[160:163], v194 offset:59392
	ds_read_b128 v[164:167], v194 offset:59408
	v_fmac_f32_e32 v68, v201, v63
	v_fmac_f32_e32 v68, v202, v64
	v_add_f32_e32 v69, 0, v69
	v_fmac_f32_e32 v68, v203, v65
	v_add_f32_e32 v66, v69, v66
	s_waitcnt lgkmcnt(9)
	v_mul_f32_e32 v69, v205, v47
	v_fmac_f32_e32 v69, v204, v46
	v_fmac_f32_e32 v69, v206, v58
	v_fmac_f32_e32 v69, v207, v59
	s_waitcnt lgkmcnt(8)
	v_fmac_f32_e32 v69, v208, v62
	ds_read_b128 v[196:199], v194 offset:4096
	ds_read_b128 v[200:203], v194 offset:4112
	v_fmac_f32_e32 v69, v209, v63
	v_fmac_f32_e32 v69, v210, v64
	v_add_f32_e32 v70, 0, v70
	v_fmac_f32_e32 v69, v211, v65
	v_add_f32_e32 v67, v70, v67
	s_waitcnt lgkmcnt(9)
	v_mul_f32_e32 v70, v137, v47
	v_fmac_f32_e32 v70, v136, v46
	v_fmac_f32_e32 v70, v138, v58
	v_fmac_f32_e32 v70, v139, v59
	s_waitcnt lgkmcnt(8)
	v_fmac_f32_e32 v70, v140, v62
	ds_read_b128 v[204:207], v194 offset:12288
	ds_read_b128 v[208:211], v194 offset:12304
	v_fmac_f32_e32 v70, v141, v63
	v_fmac_f32_e32 v70, v142, v64
	v_add_f32_e32 v71, 0, v71
	v_fmac_f32_e32 v70, v143, v65
	v_add_f32_e32 v68, v71, v68
	s_waitcnt lgkmcnt(9)
	v_mul_f32_e32 v71, v145, v47
	v_fmac_f32_e32 v71, v144, v46
	v_fmac_f32_e32 v71, v146, v58
	v_fmac_f32_e32 v71, v147, v59
	s_waitcnt lgkmcnt(8)
	v_fmac_f32_e32 v71, v148, v62
	ds_read_b128 v[136:139], v194 offset:20480
	ds_read_b128 v[140:143], v194 offset:20496
	v_fmac_f32_e32 v71, v149, v63
	v_fmac_f32_e32 v71, v150, v64
	v_add_f32_e32 v72, 0, v72
	v_fmac_f32_e32 v71, v151, v65
	v_add_f32_e32 v69, v72, v69
	s_waitcnt lgkmcnt(9)
	v_mul_f32_e32 v72, v153, v47
	v_fmac_f32_e32 v72, v152, v46
	v_fmac_f32_e32 v72, v154, v58
	v_fmac_f32_e32 v72, v155, v59
	s_waitcnt lgkmcnt(8)
	v_fmac_f32_e32 v72, v156, v62
	ds_read_b128 v[144:147], v194 offset:28672
	ds_read_b128 v[148:151], v194 offset:28688
	v_fmac_f32_e32 v72, v157, v63
	v_fmac_f32_e32 v72, v158, v64
	v_fmac_f32_e32 v72, v159, v65
	s_waitcnt lgkmcnt(9)
	v_mul_f32_e32 v47, v161, v47
	v_fmac_f32_e32 v47, v160, v46
	v_fmac_f32_e32 v47, v162, v58
	v_fmac_f32_e32 v47, v163, v59
	s_waitcnt lgkmcnt(8)
	v_fmac_f32_e32 v47, v164, v62
	v_fmac_f32_e32 v47, v165, v63
	v_fmac_f32_e32 v47, v166, v64
	v_fmac_f32_e32 v47, v167, v65
	v_add_f32_e32 v45, v45, v47
	v_lshlrev_b32_e32 v46, 16, v36
	v_and_b32_e32 v47, 0xffff0000, v36
	ds_read_b128 v[152:155], v194 offset:36864
	ds_read_b128 v[156:159], v194 offset:36880
	v_lshlrev_b32_e32 v54, 16, v37
	v_and_b32_e32 v55, 0xffff0000, v37
	v_lshlrev_b32_e32 v56, 16, v38
	v_and_b32_e32 v57, 0xffff0000, v38
	v_lshlrev_b32_e32 v58, 16, v39
	v_and_b32_e32 v59, 0xffff0000, v39
	s_waitcnt lgkmcnt(9)
	v_mul_f32_e32 v62, v197, v47
	v_fmac_f32_e32 v62, v196, v46
	v_fmac_f32_e32 v62, v198, v54
	v_fmac_f32_e32 v62, v199, v55
	s_waitcnt lgkmcnt(8)
	v_fmac_f32_e32 v62, v200, v56
	ds_read_b128 v[160:163], v194 offset:45056
	ds_read_b128 v[164:167], v194 offset:45072
	v_fmac_f32_e32 v62, v201, v57
	v_fmac_f32_e32 v62, v202, v58
	v_fmac_f32_e32 v62, v203, v59
	s_waitcnt lgkmcnt(9)
	v_mul_f32_e32 v63, v205, v47
	v_fmac_f32_e32 v63, v204, v46
	v_fmac_f32_e32 v63, v206, v54
	v_fmac_f32_e32 v63, v207, v55
	s_waitcnt lgkmcnt(8)
	v_fmac_f32_e32 v63, v208, v56
	ds_read_b128 v[196:199], v194 offset:53248
	ds_read_b128 v[200:203], v194 offset:53264
	v_fmac_f32_e32 v63, v209, v57
	v_fmac_f32_e32 v63, v210, v58
	v_fmac_f32_e32 v63, v211, v59
	s_waitcnt lgkmcnt(9)
	v_mul_f32_e32 v64, v137, v47
	v_fmac_f32_e32 v64, v136, v46
	v_fmac_f32_e32 v64, v138, v54
	v_fmac_f32_e32 v64, v139, v55
	s_waitcnt lgkmcnt(8)
	v_fmac_f32_e32 v64, v140, v56
	ds_read_b128 v[204:207], v194 offset:61440
	ds_read_b128 v[208:211], v194 offset:61456
	v_fmac_f32_e32 v64, v141, v57
	v_fmac_f32_e32 v64, v142, v58
	v_fmac_f32_e32 v64, v143, v59
	s_waitcnt lgkmcnt(9)
	v_mul_f32_e32 v65, v145, v47
	v_fmac_f32_e32 v65, v144, v46
	v_fmac_f32_e32 v65, v146, v54
	v_fmac_f32_e32 v65, v147, v55
	s_waitcnt lgkmcnt(8)
	v_fmac_f32_e32 v65, v148, v56
	ds_read_b128 v[136:139], v194 offset:6144
	ds_read_b128 v[140:143], v194 offset:6160
	v_fmac_f32_e32 v65, v149, v57
	v_fmac_f32_e32 v65, v150, v58
	v_fmac_f32_e32 v65, v151, v59
	v_add_f32_e32 v62, v66, v62
	s_waitcnt lgkmcnt(9)
	v_mul_f32_e32 v66, v153, v47
	v_fmac_f32_e32 v66, v152, v46
	v_fmac_f32_e32 v66, v154, v54
	v_fmac_f32_e32 v66, v155, v55
	s_waitcnt lgkmcnt(8)
	v_fmac_f32_e32 v66, v156, v56
	ds_read_b128 v[144:147], v194 offset:14336
	ds_read_b128 v[148:151], v194 offset:14352
	v_fmac_f32_e32 v66, v157, v57
	v_fmac_f32_e32 v66, v158, v58
	v_fmac_f32_e32 v66, v159, v59
	v_add_f32_e32 v63, v67, v63
	s_waitcnt lgkmcnt(9)
	v_mul_f32_e32 v67, v161, v47
	v_fmac_f32_e32 v67, v160, v46
	v_fmac_f32_e32 v67, v162, v54
	v_fmac_f32_e32 v67, v163, v55
	s_waitcnt lgkmcnt(8)
	v_fmac_f32_e32 v67, v164, v56
	ds_read_b128 v[152:155], v194 offset:22528
	ds_read_b128 v[156:159], v194 offset:22544
	v_fmac_f32_e32 v67, v165, v57
	v_fmac_f32_e32 v67, v166, v58
	v_fmac_f32_e32 v67, v167, v59
	v_add_f32_e32 v64, v68, v64
	s_waitcnt lgkmcnt(9)
	v_mul_f32_e32 v68, v197, v47
	v_fmac_f32_e32 v68, v196, v46
	v_fmac_f32_e32 v68, v198, v54
	v_fmac_f32_e32 v68, v199, v55
	s_waitcnt lgkmcnt(8)
	v_fmac_f32_e32 v68, v200, v56
	ds_read_b128 v[160:163], v194 offset:30720
	ds_read_b128 v[164:167], v194 offset:30736
	v_fmac_f32_e32 v68, v201, v57
	v_fmac_f32_e32 v68, v202, v58
	v_fmac_f32_e32 v68, v203, v59
	s_waitcnt lgkmcnt(9)
	v_mul_f32_e32 v41, v205, v47
	v_fmac_f32_e32 v41, v204, v46
	v_fmac_f32_e32 v41, v206, v54
	v_fmac_f32_e32 v41, v207, v55
	s_waitcnt lgkmcnt(8)
	v_fmac_f32_e32 v41, v208, v56
	v_fmac_f32_e32 v41, v209, v57
	v_fmac_f32_e32 v41, v210, v58
	v_fmac_f32_e32 v41, v211, v59
	v_add_f32_e32 v40, v45, v41
	v_lshlrev_b32_e32 v41, 16, v32
	v_and_b32_e32 v42, 0xffff0000, v32
	ds_read_b128 v[196:199], v194 offset:38912
	ds_read_b128 v[200:203], v194 offset:38928
	v_lshlrev_b32_e32 v43, 16, v33
	v_and_b32_e32 v45, 0xffff0000, v33
	v_lshlrev_b32_e32 v46, 16, v34
	v_and_b32_e32 v47, 0xffff0000, v34
	v_lshlrev_b32_e32 v54, 16, v35
	v_and_b32_e32 v55, 0xffff0000, v35
	s_waitcnt lgkmcnt(9)
	v_mul_f32_e32 v56, v137, v42
	v_fmac_f32_e32 v56, v136, v41
	v_fmac_f32_e32 v56, v138, v43
	v_fmac_f32_e32 v56, v139, v45
	s_waitcnt lgkmcnt(8)
	v_fmac_f32_e32 v56, v140, v46
	ds_read_b128 v[204:207], v194 offset:47104
	ds_read_b128 v[208:211], v194 offset:47120
	v_fmac_f32_e32 v56, v141, v47
	v_fmac_f32_e32 v56, v142, v54
	v_fmac_f32_e32 v56, v143, v55
	s_waitcnt lgkmcnt(9)
	v_mul_f32_e32 v57, v145, v42
	v_fmac_f32_e32 v57, v144, v41
	v_fmac_f32_e32 v57, v146, v43
	v_fmac_f32_e32 v57, v147, v45
	s_waitcnt lgkmcnt(8)
	v_fmac_f32_e32 v57, v148, v46
	ds_read_b128 v[136:139], v194 offset:55296
	ds_read_b128 v[140:143], v194 offset:55312
	v_fmac_f32_e32 v57, v149, v47
	v_fmac_f32_e32 v57, v150, v54
	v_fmac_f32_e32 v57, v151, v55
	s_waitcnt lgkmcnt(9)
	v_mul_f32_e32 v58, v153, v42
	v_fmac_f32_e32 v58, v152, v41
	v_fmac_f32_e32 v58, v154, v43
	v_fmac_f32_e32 v58, v155, v45
	s_waitcnt lgkmcnt(8)
	v_fmac_f32_e32 v58, v156, v46
	ds_read_b128 v[144:147], v194 offset:63488
	ds_read_b128 v[148:151], v194 offset:63504
	v_fmac_f32_e32 v58, v157, v47
	v_fmac_f32_e32 v58, v158, v54
	v_fmac_f32_e32 v58, v159, v55
	s_waitcnt lgkmcnt(9)
	v_mul_f32_e32 v59, v161, v42
	v_fmac_f32_e32 v59, v160, v41
	v_fmac_f32_e32 v59, v162, v43
	v_fmac_f32_e32 v59, v163, v45
	s_waitcnt lgkmcnt(8)
	v_fmac_f32_e32 v59, v164, v46
	v_fmac_f32_e32 v59, v165, v47
	v_fmac_f32_e32 v59, v166, v54
	v_fmac_f32_e32 v59, v167, v55
	v_add_f32_e32 v56, v62, v56
	s_waitcnt lgkmcnt(7)
	v_mul_f32_e32 v62, v197, v42
	v_fmac_f32_e32 v62, v196, v41
	v_fmac_f32_e32 v62, v198, v43
	v_fmac_f32_e32 v62, v199, v45
	s_waitcnt lgkmcnt(6)
	v_fmac_f32_e32 v62, v200, v46
	v_fmac_f32_e32 v62, v201, v47
	v_fmac_f32_e32 v62, v202, v54
	v_fmac_f32_e32 v62, v203, v55
	v_add_f32_e32 v57, v63, v57
	s_waitcnt lgkmcnt(5)
	v_mul_f32_e32 v63, v205, v42
	v_fmac_f32_e32 v63, v204, v41
	v_fmac_f32_e32 v63, v206, v43
	v_fmac_f32_e32 v63, v207, v45
	s_waitcnt lgkmcnt(4)
	v_fmac_f32_e32 v63, v208, v46
	v_fmac_f32_e32 v63, v209, v47
	v_fmac_f32_e32 v63, v210, v54
	v_fmac_f32_e32 v63, v211, v55
	v_add_f32_e32 v58, v64, v58
	s_waitcnt lgkmcnt(3)
	v_mul_f32_e32 v64, v137, v42
	v_fmac_f32_e32 v64, v136, v41
	v_fmac_f32_e32 v64, v138, v43
	v_fmac_f32_e32 v64, v139, v45
	s_waitcnt lgkmcnt(2)
	v_fmac_f32_e32 v64, v140, v46
	v_fmac_f32_e32 v64, v141, v47
	v_fmac_f32_e32 v64, v142, v54
	v_fmac_f32_e32 v64, v143, v55
	s_waitcnt lgkmcnt(1)
	v_mul_f32_e32 v37, v145, v42
	v_fmac_f32_e32 v37, v144, v41
	v_fmac_f32_e32 v37, v146, v43
	v_fmac_f32_e32 v37, v147, v45
	s_waitcnt lgkmcnt(0)
	v_fmac_f32_e32 v37, v148, v46
	v_fmac_f32_e32 v37, v149, v47
	ds_bpermute_b32 v33, v50, v56
	v_fmac_f32_e32 v37, v150, v54
	ds_bpermute_b32 v34, v50, v57
	v_add_f32_e32 v73, 0, v73
	v_add_f32_e32 v74, 0, v74
	v_add_f32_e32 v75, 0, v75
	v_add_f32_e32 v70, v73, v70
	v_add_f32_e32 v71, v74, v71
	v_add_f32_e32 v72, v75, v72
	v_add_f32_e32 v65, v69, v65
	v_add_f32_e32 v66, v70, v66
	v_add_f32_e32 v67, v71, v67
	v_add_f32_e32 v68, v72, v68
	v_add_f32_e32 v59, v65, v59
	v_fmac_f32_e32 v37, v151, v55
	v_add_f32_e32 v62, v66, v62
	v_add_f32_e32 v63, v67, v63
	v_add_f32_e32 v44, v68, v64
	v_add_f32_e32 v32, v40, v37
	ds_bpermute_b32 v35, v50, v58
	ds_bpermute_b32 v36, v50, v59
	s_waitcnt lgkmcnt(3)
	v_add_f32_e32 v33, v56, v33
	ds_bpermute_b32 v37, v50, v62
	s_waitcnt lgkmcnt(3)
	v_add_f32_e32 v34, v57, v34
	ds_bpermute_b32 v38, v50, v63
	ds_bpermute_b32 v39, v50, v44
	ds_bpermute_b32 v40, v50, v32
	ds_bpermute_b32 v41, v48, v33
	ds_bpermute_b32 v42, v48, v34
	s_waitcnt lgkmcnt(7)
	v_add_f32_e32 v35, v58, v35
	s_waitcnt lgkmcnt(6)
	v_add_f32_e32 v36, v59, v36
	s_waitcnt lgkmcnt(5)
	v_add_f32_e32 v37, v62, v37
	s_waitcnt lgkmcnt(4)
	v_add_f32_e32 v38, v63, v38
	s_waitcnt lgkmcnt(3)
	v_add_f32_e32 v39, v44, v39
	s_waitcnt lgkmcnt(2)
	v_add_f32_e32 v32, v32, v40
	s_waitcnt lgkmcnt(1)
	v_add_f32_e32 v33, v33, v41
	ds_bpermute_b32 v40, v48, v35
	ds_bpermute_b32 v41, v48, v36
	s_waitcnt lgkmcnt(2)
	v_add_f32_e32 v34, v34, v42
	ds_bpermute_b32 v42, v48, v37
	ds_bpermute_b32 v43, v48, v38
	ds_bpermute_b32 v44, v48, v39
	s_waitcnt lgkmcnt(4)
	v_add_f32_e32 v35, v35, v40
	s_waitcnt lgkmcnt(3)
	v_add_f32_e32 v36, v36, v41
	ds_bpermute_b32 v40, v48, v32
	ds_bpermute_b32 v41, v51, v33
	s_waitcnt lgkmcnt(4)
	v_add_f32_e32 v37, v37, v42
	s_waitcnt lgkmcnt(3)
	v_add_f32_e32 v38, v38, v43
	s_waitcnt lgkmcnt(2)
	v_add_f32_e32 v39, v39, v44
	ds_bpermute_b32 v42, v51, v34
	ds_bpermute_b32 v43, v51, v35
	ds_bpermute_b32 v44, v51, v36
	s_waitcnt lgkmcnt(4)
	v_add_f32_e32 v32, v32, v40
	s_waitcnt lgkmcnt(3)
	v_add_f32_e32 v33, v33, v41
	ds_bpermute_b32 v40, v51, v37
	ds_bpermute_b32 v41, v51, v38
	s_waitcnt lgkmcnt(4)
	v_add_f32_e32 v34, v34, v42
	s_waitcnt lgkmcnt(3)
	v_add_f32_e32 v35, v35, v43
	s_waitcnt lgkmcnt(2)
	v_add_f32_e32 v36, v36, v44
	ds_bpermute_b32 v42, v51, v39
	ds_bpermute_b32 v43, v51, v32
	ds_bpermute_b32 v44, v49, v33
	s_waitcnt lgkmcnt(4)
	v_add_f32_e32 v37, v37, v40
	s_waitcnt lgkmcnt(3)
	v_add_f32_e32 v38, v38, v41
	ds_bpermute_b32 v40, v49, v34
	ds_bpermute_b32 v41, v49, v35
	s_waitcnt lgkmcnt(4)
	v_add_f32_e32 v39, v39, v42
	s_waitcnt lgkmcnt(3)
	v_add_f32_e32 v32, v32, v43
	s_waitcnt lgkmcnt(2)
	v_add_f32_e32 v33, v33, v44
	ds_bpermute_b32 v42, v49, v36
	ds_bpermute_b32 v43, v49, v37
	ds_bpermute_b32 v44, v49, v38
	s_waitcnt lgkmcnt(4)
	v_add_f32_e32 v34, v34, v40
	s_waitcnt lgkmcnt(3)
	v_add_f32_e32 v35, v35, v41
	ds_bpermute_b32 v40, v49, v39
	ds_bpermute_b32 v41, v49, v32
	s_waitcnt lgkmcnt(4)
	v_add_f32_e32 v36, v36, v42
	s_waitcnt lgkmcnt(3)
	v_add_f32_e32 v37, v37, v43
	s_waitcnt lgkmcnt(2)
	v_add_f32_e32 v38, v38, v44
	ds_bpermute_b32 v42, v52, v33
	ds_bpermute_b32 v43, v52, v34
	ds_bpermute_b32 v44, v52, v35
	s_waitcnt lgkmcnt(4)
	v_add_f32_e32 v39, v39, v40
	s_waitcnt lgkmcnt(3)
	v_add_f32_e32 v41, v32, v41
	s_waitcnt lgkmcnt(2)
	v_add_f32_e32 v32, v33, v42
	s_waitcnt lgkmcnt(1)
	v_add_f32_e32 v33, v34, v43
	s_waitcnt lgkmcnt(0)
	v_add_f32_e32 v34, v35, v44
	ds_bpermute_b32 v35, v52, v36
	ds_bpermute_b32 v40, v52, v37
	ds_bpermute_b32 v42, v52, v38
	ds_bpermute_b32 v43, v52, v39
	ds_bpermute_b32 v44, v52, v41
	s_waitcnt lgkmcnt(4)
	v_add_f32_e32 v35, v36, v35
	s_waitcnt lgkmcnt(3)
	v_add_f32_e32 v36, v37, v40
	s_waitcnt lgkmcnt(2)
	v_add_f32_e32 v38, v38, v42
	s_waitcnt lgkmcnt(1)
	v_add_f32_e32 v40, v39, v43
	s_waitcnt lgkmcnt(0)
	v_add_f32_e32 v42, v41, v44
	ds_bpermute_b32 v37, v53, v32
	ds_bpermute_b32 v39, v53, v33
	ds_bpermute_b32 v41, v53, v34
	ds_bpermute_b32 v43, v53, v35
	ds_bpermute_b32 v44, v53, v36
	ds_bpermute_b32 v45, v53, v38
	ds_bpermute_b32 v46, v53, v40
	ds_bpermute_b32 v47, v53, v42
	s_and_b64 s[4:5], s[38:39], s[56:57]
	s_and_saveexec_b64 s[0:1], s[4:5]
	s_cbranch_execz .LBB0_645
	s_waitcnt lgkmcnt(6)
	v_add_f32_e32 v33, v33, v39
	v_add_f32_e32 v32, v32, v37
	s_waitcnt lgkmcnt(5)
	v_add_f32_e32 v34, v34, v41
	v_cndmask_b32_e64 v32, v32, v33, s[42:43]
	s_waitcnt lgkmcnt(4)
	v_add_f32_e32 v35, v35, v43
	v_cndmask_b32_e64 v32, v32, v34, s[44:45]
	s_waitcnt lgkmcnt(3)
	v_add_f32_e32 v36, v36, v44
	v_cndmask_b32_e64 v32, v32, v35, s[46:47]
	s_waitcnt lgkmcnt(2)
	v_add_f32_e32 v38, v38, v45
	v_cndmask_b32_e64 v32, v32, v36, s[48:49]
	s_waitcnt lgkmcnt(1)
	v_add_f32_e32 v40, v40, v46
	v_cndmask_b32_e64 v32, v32, v38, s[50:51]
	s_waitcnt lgkmcnt(0)
	v_add_f32_e32 v42, v42, v47
	v_cndmask_b32_e64 v32, v32, v40, s[52:53]
	v_cndmask_b32_e64 v34, v32, v42, s[54:55]
	v_lshlrev_b64 v[32:33], 5, v[100:101]
	v_lshl_add_u64 v[32:33], v[60:61], 0, v[32:33]
	global_store_dword v[32:33], v34, off
.LBB0_645:
	s_or_b64 exec, exec, s[0:1]
	v_mov_b32_e32 v32, v104
	v_lshlrev_b32_e32 v40, 16, v28
	s_waitcnt lgkmcnt(5)
	v_and_b32_e32 v41, 0xffff0000, v28
	v_lshlrev_b32_e32 v28, 2, v32
	v_and_b32_e32 v194, -16, v28
	ds_read_b128 v[136:139], v194
	ds_read_b128 v[140:143], v194 offset:16
	ds_read_b128 v[144:147], v194 offset:8192
	ds_read_b128 v[148:151], v194 offset:8208
	ds_read_b128 v[152:155], v194 offset:16384
	ds_read_b128 v[156:159], v194 offset:16400
	ds_read_b128 v[160:163], v194 offset:24576
	ds_read_b128 v[164:167], v194 offset:24592
	ds_read_b128 v[196:199], v194 offset:32768
	ds_read_b128 v[200:203], v194 offset:32784
	v_lshlrev_b32_e32 v43, 16, v30
	v_and_b32_e32 v44, 0xffff0000, v30
	s_waitcnt lgkmcnt(9)
	v_mul_f32_e32 v47, v137, v41
	v_lshlrev_b32_e32 v42, 16, v29
	v_fmac_f32_e32 v47, v136, v40
	v_fmac_f32_e32 v47, v138, v42
	v_and_b32_e32 v29, 0xffff0000, v29
	v_lshlrev_b32_e32 v45, 16, v31
	v_and_b32_e32 v46, 0xffff0000, v31
	ds_read_b128 v[204:207], v194 offset:40960
	ds_read_b128 v[208:211], v194 offset:40976
	v_fmac_f32_e32 v47, v139, v29
	s_waitcnt lgkmcnt(10)
	v_fmac_f32_e32 v47, v140, v43
	v_fmac_f32_e32 v47, v141, v44
	v_fmac_f32_e32 v47, v142, v45
	v_fmac_f32_e32 v47, v143, v46
	s_waitcnt lgkmcnt(9)
	v_mul_f32_e32 v39, v145, v41
	v_fmac_f32_e32 v39, v144, v40
	v_fmac_f32_e32 v39, v146, v42
	v_fmac_f32_e32 v39, v147, v29
	s_waitcnt lgkmcnt(8)
	v_fmac_f32_e32 v39, v148, v43
	ds_read_b128 v[136:139], v194 offset:49152
	ds_read_b128 v[140:143], v194 offset:49168
	v_fmac_f32_e32 v39, v149, v44
	v_fmac_f32_e32 v39, v150, v45
	v_fmac_f32_e32 v39, v151, v46
	v_add_f32_e32 v38, 0, v47
	s_waitcnt lgkmcnt(9)
	v_mul_f32_e32 v47, v153, v41
	v_fmac_f32_e32 v47, v152, v40
	v_fmac_f32_e32 v47, v154, v42
	v_fmac_f32_e32 v47, v155, v29
	s_waitcnt lgkmcnt(8)
	v_fmac_f32_e32 v47, v156, v43
	ds_read_b128 v[144:147], v194 offset:57344
	ds_read_b128 v[148:151], v194 offset:57360
	v_fmac_f32_e32 v47, v157, v44
	v_fmac_f32_e32 v47, v158, v45
	v_fmac_f32_e32 v47, v159, v46
	s_waitcnt lgkmcnt(9)
	v_mul_f32_e32 v54, v161, v41
	v_fmac_f32_e32 v54, v160, v40
	v_fmac_f32_e32 v54, v162, v42
	v_fmac_f32_e32 v54, v163, v29
	s_waitcnt lgkmcnt(8)
	v_fmac_f32_e32 v54, v164, v43
	ds_read_b128 v[152:155], v194 offset:2048
	ds_read_b128 v[156:159], v194 offset:2064
	v_fmac_f32_e32 v54, v165, v44
	v_fmac_f32_e32 v54, v166, v45
	v_fmac_f32_e32 v54, v167, v46
	s_waitcnt lgkmcnt(9)
	v_mul_f32_e32 v55, v197, v41
	v_fmac_f32_e32 v55, v196, v40
	v_fmac_f32_e32 v55, v198, v42
	v_fmac_f32_e32 v55, v199, v29
	s_waitcnt lgkmcnt(8)
	v_fmac_f32_e32 v55, v200, v43
	ds_read_b128 v[160:163], v194 offset:10240
	ds_read_b128 v[164:167], v194 offset:10256
	v_fmac_f32_e32 v55, v201, v44
	v_fmac_f32_e32 v55, v202, v45
	v_fmac_f32_e32 v55, v203, v46
	s_waitcnt lgkmcnt(9)
	v_mul_f32_e32 v56, v205, v41
	v_fmac_f32_e32 v56, v204, v40
	v_fmac_f32_e32 v56, v206, v42
	v_fmac_f32_e32 v56, v207, v29
	s_waitcnt lgkmcnt(8)
	v_fmac_f32_e32 v56, v208, v43
	ds_read_b128 v[196:199], v194 offset:18432
	ds_read_b128 v[200:203], v194 offset:18448
	v_fmac_f32_e32 v56, v209, v44
	v_fmac_f32_e32 v56, v210, v45
	v_fmac_f32_e32 v56, v211, v46
	s_waitcnt lgkmcnt(9)
	v_mul_f32_e32 v57, v137, v41
	v_fmac_f32_e32 v57, v136, v40
	v_fmac_f32_e32 v57, v138, v42
	v_fmac_f32_e32 v57, v139, v29
	s_waitcnt lgkmcnt(8)
	v_fmac_f32_e32 v57, v140, v43
	ds_read_b128 v[204:207], v194 offset:26624
	ds_read_b128 v[208:211], v194 offset:26640
	v_fmac_f32_e32 v57, v141, v44
	v_fmac_f32_e32 v57, v142, v45
	v_fmac_f32_e32 v57, v143, v46
	s_waitcnt lgkmcnt(9)
	v_mul_f32_e32 v31, v145, v41
	v_fmac_f32_e32 v31, v144, v40
	v_fmac_f32_e32 v31, v146, v42
	v_fmac_f32_e32 v31, v147, v29
	s_waitcnt lgkmcnt(8)
	v_fmac_f32_e32 v31, v148, v43
	v_fmac_f32_e32 v31, v149, v44
	v_lshlrev_b32_e32 v34, 16, v24
	v_and_b32_e32 v35, 0xffff0000, v24
	v_fmac_f32_e32 v31, v150, v45
	v_fmac_f32_e32 v31, v151, v46
	v_add_f32_e32 v29, 0, v31
	ds_read_b128 v[136:139], v194 offset:34816
	ds_read_b128 v[140:143], v194 offset:34832
	v_lshlrev_b32_e32 v36, 16, v25
	v_and_b32_e32 v37, 0xffff0000, v25
	v_lshlrev_b32_e32 v40, 16, v26
	v_and_b32_e32 v41, 0xffff0000, v26
	v_lshlrev_b32_e32 v42, 16, v27
	v_and_b32_e32 v43, 0xffff0000, v27
	s_waitcnt lgkmcnt(9)
	v_mul_f32_e32 v44, v153, v35
	v_fmac_f32_e32 v44, v152, v34
	v_fmac_f32_e32 v44, v154, v36
	v_fmac_f32_e32 v44, v155, v37
	s_waitcnt lgkmcnt(8)
	v_fmac_f32_e32 v44, v156, v40
	ds_read_b128 v[144:147], v194 offset:43008
	ds_read_b128 v[148:151], v194 offset:43024
	v_fmac_f32_e32 v44, v157, v41
	v_fmac_f32_e32 v44, v158, v42
	v_fmac_f32_e32 v44, v159, v43
	v_add_f32_e32 v38, v38, v44
	s_waitcnt lgkmcnt(9)
	v_mul_f32_e32 v44, v161, v35
	v_fmac_f32_e32 v44, v160, v34
	v_fmac_f32_e32 v44, v162, v36
	v_fmac_f32_e32 v44, v163, v37
	s_waitcnt lgkmcnt(8)
	v_fmac_f32_e32 v44, v164, v40
	ds_read_b128 v[152:155], v194 offset:51200
	ds_read_b128 v[156:159], v194 offset:51216
	v_fmac_f32_e32 v44, v165, v41
	v_fmac_f32_e32 v44, v166, v42
	v_add_f32_e32 v39, 0, v39
	v_fmac_f32_e32 v44, v167, v43
	v_add_f32_e32 v39, v39, v44
	s_waitcnt lgkmcnt(9)
	v_mul_f32_e32 v44, v197, v35
	v_fmac_f32_e32 v44, v196, v34
	v_fmac_f32_e32 v44, v198, v36
	v_fmac_f32_e32 v44, v199, v37
	s_waitcnt lgkmcnt(8)
	v_fmac_f32_e32 v44, v200, v40
	ds_read_b128 v[160:163], v194 offset:59392
	ds_read_b128 v[164:167], v194 offset:59408
	v_fmac_f32_e32 v44, v201, v41
	v_fmac_f32_e32 v44, v202, v42
	v_fmac_f32_e32 v44, v203, v43
	s_waitcnt lgkmcnt(9)
	v_mul_f32_e32 v45, v205, v35
	v_fmac_f32_e32 v45, v204, v34
	v_fmac_f32_e32 v45, v206, v36
	v_fmac_f32_e32 v45, v207, v37
	s_waitcnt lgkmcnt(8)
	v_fmac_f32_e32 v45, v208, v40
	ds_read_b128 v[196:199], v194 offset:4096
	ds_read_b128 v[200:203], v194 offset:4112
	v_fmac_f32_e32 v45, v209, v41
	v_fmac_f32_e32 v45, v210, v42
	v_fmac_f32_e32 v45, v211, v43
	s_waitcnt lgkmcnt(9)
	v_mul_f32_e32 v46, v137, v35
	v_fmac_f32_e32 v46, v136, v34
	v_fmac_f32_e32 v46, v138, v36
	v_fmac_f32_e32 v46, v139, v37
	s_waitcnt lgkmcnt(8)
	v_fmac_f32_e32 v46, v140, v40
	ds_read_b128 v[204:207], v194 offset:12288
	ds_read_b128 v[208:211], v194 offset:12304
	v_fmac_f32_e32 v46, v141, v41
	v_fmac_f32_e32 v46, v142, v42
	v_add_f32_e32 v47, 0, v47
	v_fmac_f32_e32 v46, v143, v43
	v_add_f32_e32 v44, v47, v44
	s_waitcnt lgkmcnt(9)
	v_mul_f32_e32 v47, v145, v35
	v_fmac_f32_e32 v47, v144, v34
	v_fmac_f32_e32 v47, v146, v36
	v_fmac_f32_e32 v47, v147, v37
	s_waitcnt lgkmcnt(8)
	v_fmac_f32_e32 v47, v148, v40
	ds_read_b128 v[136:139], v194 offset:20480
	ds_read_b128 v[140:143], v194 offset:20496
	v_fmac_f32_e32 v47, v149, v41
	v_fmac_f32_e32 v47, v150, v42
	v_add_f32_e32 v54, 0, v54
	v_fmac_f32_e32 v47, v151, v43
	v_add_f32_e32 v45, v54, v45
	s_waitcnt lgkmcnt(9)
	v_mul_f32_e32 v54, v153, v35
	v_fmac_f32_e32 v54, v152, v34
	v_fmac_f32_e32 v54, v154, v36
	v_fmac_f32_e32 v54, v155, v37
	s_waitcnt lgkmcnt(8)
	v_fmac_f32_e32 v54, v156, v40
	ds_read_b128 v[144:147], v194 offset:28672
	ds_read_b128 v[148:151], v194 offset:28688
	v_fmac_f32_e32 v54, v157, v41
	v_fmac_f32_e32 v54, v158, v42
	v_fmac_f32_e32 v54, v159, v43
	s_waitcnt lgkmcnt(9)
	v_mul_f32_e32 v31, v161, v35
	v_fmac_f32_e32 v31, v160, v34
	v_fmac_f32_e32 v31, v162, v36
	v_fmac_f32_e32 v31, v163, v37
	s_waitcnt lgkmcnt(8)
	v_fmac_f32_e32 v31, v164, v40
	v_fmac_f32_e32 v31, v165, v41
	v_fmac_f32_e32 v31, v166, v42
	v_fmac_f32_e32 v31, v167, v43
	v_add_f32_e32 v29, v29, v31
	v_lshlrev_b32_e32 v30, 16, v20
	v_and_b32_e32 v31, 0xffff0000, v20
	ds_read_b128 v[152:155], v194 offset:36864
	ds_read_b128 v[156:159], v194 offset:36880
	v_lshlrev_b32_e32 v32, 16, v21
	v_and_b32_e32 v33, 0xffff0000, v21
	v_lshlrev_b32_e32 v34, 16, v22
	v_and_b32_e32 v35, 0xffff0000, v22
	v_lshlrev_b32_e32 v36, 16, v23
	v_and_b32_e32 v37, 0xffff0000, v23
	s_waitcnt lgkmcnt(9)
	v_mul_f32_e32 v40, v197, v31
	v_fmac_f32_e32 v40, v196, v30
	v_fmac_f32_e32 v40, v198, v32
	v_fmac_f32_e32 v40, v199, v33
	s_waitcnt lgkmcnt(8)
	v_fmac_f32_e32 v40, v200, v34
	ds_read_b128 v[160:163], v194 offset:45056
	ds_read_b128 v[164:167], v194 offset:45072
	v_fmac_f32_e32 v40, v201, v35
	v_fmac_f32_e32 v40, v202, v36
	v_fmac_f32_e32 v40, v203, v37
	v_add_f32_e32 v38, v38, v40
	s_waitcnt lgkmcnt(9)
	v_mul_f32_e32 v40, v205, v31
	v_fmac_f32_e32 v40, v204, v30
	v_fmac_f32_e32 v40, v206, v32
	v_fmac_f32_e32 v40, v207, v33
	s_waitcnt lgkmcnt(8)
	v_fmac_f32_e32 v40, v208, v34
	ds_read_b128 v[196:199], v194 offset:53248
	ds_read_b128 v[200:203], v194 offset:53264
	v_fmac_f32_e32 v40, v209, v35
	v_fmac_f32_e32 v40, v210, v36
	v_fmac_f32_e32 v40, v211, v37
	v_add_f32_e32 v39, v39, v40
	s_waitcnt lgkmcnt(9)
	v_mul_f32_e32 v40, v137, v31
	v_fmac_f32_e32 v40, v136, v30
	v_fmac_f32_e32 v40, v138, v32
	v_fmac_f32_e32 v40, v139, v33
	s_waitcnt lgkmcnt(8)
	v_fmac_f32_e32 v40, v140, v34
	ds_read_b128 v[204:207], v194 offset:61440
	ds_read_b128 v[208:211], v194 offset:61456
	v_fmac_f32_e32 v40, v141, v35
	v_fmac_f32_e32 v40, v142, v36
	v_fmac_f32_e32 v40, v143, v37
	s_waitcnt lgkmcnt(9)
	v_mul_f32_e32 v41, v145, v31
	v_fmac_f32_e32 v41, v144, v30
	v_fmac_f32_e32 v41, v146, v32
	v_fmac_f32_e32 v41, v147, v33
	s_waitcnt lgkmcnt(8)
	v_fmac_f32_e32 v41, v148, v34
	ds_read_b128 v[136:139], v194 offset:6144
	ds_read_b128 v[140:143], v194 offset:6160
	v_fmac_f32_e32 v41, v149, v35
	v_fmac_f32_e32 v41, v150, v36
	v_fmac_f32_e32 v41, v151, v37
	s_waitcnt lgkmcnt(9)
	v_mul_f32_e32 v42, v153, v31
	v_fmac_f32_e32 v42, v152, v30
	v_fmac_f32_e32 v42, v154, v32
	v_fmac_f32_e32 v42, v155, v33
	s_waitcnt lgkmcnt(8)
	v_fmac_f32_e32 v42, v156, v34
	ds_read_b128 v[144:147], v194 offset:14336
	ds_read_b128 v[148:151], v194 offset:14352
	v_fmac_f32_e32 v42, v157, v35
	v_fmac_f32_e32 v42, v158, v36
	v_fmac_f32_e32 v42, v159, v37
	s_waitcnt lgkmcnt(9)
	v_mul_f32_e32 v43, v161, v31
	v_fmac_f32_e32 v43, v160, v30
	v_fmac_f32_e32 v43, v162, v32
	v_fmac_f32_e32 v43, v163, v33
	s_waitcnt lgkmcnt(8)
	v_fmac_f32_e32 v43, v164, v34
	ds_read_b128 v[152:155], v194 offset:22528
	ds_read_b128 v[156:159], v194 offset:22544
	v_fmac_f32_e32 v43, v165, v35
	v_fmac_f32_e32 v43, v166, v36
	v_fmac_f32_e32 v43, v167, v37
	v_add_f32_e32 v40, v44, v40
	s_waitcnt lgkmcnt(9)
	v_mul_f32_e32 v44, v197, v31
	v_fmac_f32_e32 v44, v196, v30
	v_fmac_f32_e32 v44, v198, v32
	v_fmac_f32_e32 v44, v199, v33
	s_waitcnt lgkmcnt(8)
	v_fmac_f32_e32 v44, v200, v34
	ds_read_b128 v[160:163], v194 offset:30720
	ds_read_b128 v[164:167], v194 offset:30736
	v_fmac_f32_e32 v44, v201, v35
	v_fmac_f32_e32 v44, v202, v36
	v_fmac_f32_e32 v44, v203, v37
	s_waitcnt lgkmcnt(9)
	v_mul_f32_e32 v25, v205, v31
	v_fmac_f32_e32 v25, v204, v30
	v_fmac_f32_e32 v25, v206, v32
	v_fmac_f32_e32 v25, v207, v33
	s_waitcnt lgkmcnt(8)
	v_fmac_f32_e32 v25, v208, v34
	v_fmac_f32_e32 v25, v209, v35
	v_fmac_f32_e32 v25, v210, v36
	v_fmac_f32_e32 v25, v211, v37
	v_add_f32_e32 v24, v29, v25
	v_lshlrev_b32_e32 v25, 16, v16
	v_and_b32_e32 v26, 0xffff0000, v16
	ds_read_b128 v[196:199], v194 offset:38912
	ds_read_b128 v[200:203], v194 offset:38928
	v_lshlrev_b32_e32 v27, 16, v17
	v_and_b32_e32 v29, 0xffff0000, v17
	v_lshlrev_b32_e32 v30, 16, v18
	v_and_b32_e32 v31, 0xffff0000, v18
	v_lshlrev_b32_e32 v32, 16, v19
	v_and_b32_e32 v33, 0xffff0000, v19
	s_waitcnt lgkmcnt(9)
	v_mul_f32_e32 v34, v137, v26
	v_fmac_f32_e32 v34, v136, v25
	v_fmac_f32_e32 v34, v138, v27
	v_fmac_f32_e32 v34, v139, v29
	s_waitcnt lgkmcnt(8)
	v_fmac_f32_e32 v34, v140, v30
	ds_read_b128 v[204:207], v194 offset:47104
	ds_read_b128 v[208:211], v194 offset:47120
	v_fmac_f32_e32 v34, v141, v31
	v_fmac_f32_e32 v34, v142, v32
	v_fmac_f32_e32 v34, v143, v33
	s_waitcnt lgkmcnt(9)
	v_mul_f32_e32 v35, v145, v26
	v_fmac_f32_e32 v35, v144, v25
	v_fmac_f32_e32 v35, v146, v27
	v_fmac_f32_e32 v35, v147, v29
	s_waitcnt lgkmcnt(8)
	v_fmac_f32_e32 v35, v148, v30
	ds_read_b128 v[136:139], v194 offset:55296
	ds_read_b128 v[140:143], v194 offset:55312
	v_fmac_f32_e32 v35, v149, v31
	v_fmac_f32_e32 v35, v150, v32
	v_fmac_f32_e32 v35, v151, v33
	s_waitcnt lgkmcnt(9)
	v_mul_f32_e32 v36, v153, v26
	v_fmac_f32_e32 v36, v152, v25
	v_fmac_f32_e32 v36, v154, v27
	v_fmac_f32_e32 v36, v155, v29
	s_waitcnt lgkmcnt(8)
	v_fmac_f32_e32 v36, v156, v30
	ds_read_b128 v[144:147], v194 offset:63488
	ds_read_b128 v[148:151], v194 offset:63504
	v_fmac_f32_e32 v36, v157, v31
	v_fmac_f32_e32 v36, v158, v32
	v_fmac_f32_e32 v36, v159, v33
	s_waitcnt lgkmcnt(9)
	v_mul_f32_e32 v37, v161, v26
	v_fmac_f32_e32 v37, v160, v25
	v_fmac_f32_e32 v37, v162, v27
	v_fmac_f32_e32 v37, v163, v29
	s_waitcnt lgkmcnt(8)
	v_fmac_f32_e32 v37, v164, v30
	v_fmac_f32_e32 v37, v165, v31
	v_fmac_f32_e32 v37, v166, v32
	v_fmac_f32_e32 v37, v167, v33
	v_add_f32_e32 v34, v38, v34
	s_waitcnt lgkmcnt(7)
	v_mul_f32_e32 v38, v197, v26
	v_fmac_f32_e32 v38, v196, v25
	v_fmac_f32_e32 v38, v198, v27
	v_fmac_f32_e32 v38, v199, v29
	s_waitcnt lgkmcnt(6)
	v_fmac_f32_e32 v38, v200, v30
	v_fmac_f32_e32 v38, v201, v31
	v_fmac_f32_e32 v38, v202, v32
	v_fmac_f32_e32 v38, v203, v33
	v_add_f32_e32 v35, v39, v35
	s_waitcnt lgkmcnt(5)
	v_mul_f32_e32 v39, v205, v26
	v_fmac_f32_e32 v39, v204, v25
	v_fmac_f32_e32 v39, v206, v27
	v_fmac_f32_e32 v39, v207, v29
	s_waitcnt lgkmcnt(4)
	v_fmac_f32_e32 v39, v208, v30
	v_fmac_f32_e32 v39, v209, v31
	v_fmac_f32_e32 v39, v210, v32
	v_fmac_f32_e32 v39, v211, v33
	v_add_f32_e32 v36, v40, v36
	s_waitcnt lgkmcnt(3)
	v_mul_f32_e32 v40, v137, v26
	v_fmac_f32_e32 v40, v136, v25
	v_fmac_f32_e32 v40, v138, v27
	v_fmac_f32_e32 v40, v139, v29
	s_waitcnt lgkmcnt(2)
	v_fmac_f32_e32 v40, v140, v30
	v_fmac_f32_e32 v40, v141, v31
	v_fmac_f32_e32 v40, v142, v32
	v_fmac_f32_e32 v40, v143, v33
	s_waitcnt lgkmcnt(1)
	v_mul_f32_e32 v21, v145, v26
	v_fmac_f32_e32 v21, v144, v25
	v_fmac_f32_e32 v21, v146, v27
	v_fmac_f32_e32 v21, v147, v29
	s_waitcnt lgkmcnt(0)
	v_fmac_f32_e32 v21, v148, v30
	v_fmac_f32_e32 v21, v149, v31
	ds_bpermute_b32 v17, v50, v34
	v_fmac_f32_e32 v21, v150, v32
	ds_bpermute_b32 v18, v50, v35
	v_add_f32_e32 v55, 0, v55
	v_add_f32_e32 v56, 0, v56
	v_add_f32_e32 v57, 0, v57
	v_add_f32_e32 v46, v55, v46
	v_add_f32_e32 v47, v56, v47
	v_add_f32_e32 v54, v57, v54
	v_add_f32_e32 v41, v45, v41
	v_add_f32_e32 v42, v46, v42
	v_add_f32_e32 v43, v47, v43
	v_add_f32_e32 v44, v54, v44
	v_add_f32_e32 v37, v41, v37
	v_fmac_f32_e32 v21, v151, v33
	v_add_f32_e32 v38, v42, v38
	v_add_f32_e32 v39, v43, v39
	v_add_f32_e32 v28, v44, v40
	v_add_f32_e32 v16, v24, v21
	ds_bpermute_b32 v19, v50, v36
	ds_bpermute_b32 v20, v50, v37
	s_waitcnt lgkmcnt(3)
	v_add_f32_e32 v17, v34, v17
	ds_bpermute_b32 v21, v50, v38
	s_waitcnt lgkmcnt(3)
	v_add_f32_e32 v18, v35, v18
	ds_bpermute_b32 v22, v50, v39
	ds_bpermute_b32 v23, v50, v28
	ds_bpermute_b32 v24, v50, v16
	ds_bpermute_b32 v25, v48, v17
	ds_bpermute_b32 v26, v48, v18
	s_waitcnt lgkmcnt(7)
	v_add_f32_e32 v19, v36, v19
	s_waitcnt lgkmcnt(6)
	v_add_f32_e32 v20, v37, v20
	s_waitcnt lgkmcnt(5)
	v_add_f32_e32 v21, v38, v21
	s_waitcnt lgkmcnt(4)
	v_add_f32_e32 v22, v39, v22
	s_waitcnt lgkmcnt(3)
	v_add_f32_e32 v23, v28, v23
	s_waitcnt lgkmcnt(2)
	v_add_f32_e32 v16, v16, v24
	s_waitcnt lgkmcnt(1)
	v_add_f32_e32 v17, v17, v25
	ds_bpermute_b32 v24, v48, v19
	ds_bpermute_b32 v25, v48, v20
	s_waitcnt lgkmcnt(2)
	v_add_f32_e32 v18, v18, v26
	ds_bpermute_b32 v26, v48, v21
	ds_bpermute_b32 v27, v48, v22
	ds_bpermute_b32 v28, v48, v23
	s_waitcnt lgkmcnt(4)
	v_add_f32_e32 v19, v19, v24
	s_waitcnt lgkmcnt(3)
	v_add_f32_e32 v20, v20, v25
	ds_bpermute_b32 v24, v48, v16
	ds_bpermute_b32 v25, v51, v17
	s_waitcnt lgkmcnt(4)
	v_add_f32_e32 v21, v21, v26
	s_waitcnt lgkmcnt(3)
	v_add_f32_e32 v22, v22, v27
	s_waitcnt lgkmcnt(2)
	v_add_f32_e32 v23, v23, v28
	ds_bpermute_b32 v26, v51, v18
	ds_bpermute_b32 v27, v51, v19
	ds_bpermute_b32 v28, v51, v20
	s_waitcnt lgkmcnt(4)
	v_add_f32_e32 v16, v16, v24
	s_waitcnt lgkmcnt(3)
	v_add_f32_e32 v17, v17, v25
	ds_bpermute_b32 v24, v51, v21
	ds_bpermute_b32 v25, v51, v22
	s_waitcnt lgkmcnt(4)
	v_add_f32_e32 v18, v18, v26
	s_waitcnt lgkmcnt(3)
	v_add_f32_e32 v19, v19, v27
	s_waitcnt lgkmcnt(2)
	v_add_f32_e32 v20, v20, v28
	ds_bpermute_b32 v26, v51, v23
	ds_bpermute_b32 v27, v51, v16
	ds_bpermute_b32 v28, v49, v17
	s_waitcnt lgkmcnt(4)
	v_add_f32_e32 v21, v21, v24
	s_waitcnt lgkmcnt(3)
	v_add_f32_e32 v22, v22, v25
	ds_bpermute_b32 v24, v49, v18
	ds_bpermute_b32 v25, v49, v19
	s_waitcnt lgkmcnt(4)
	v_add_f32_e32 v23, v23, v26
	s_waitcnt lgkmcnt(3)
	v_add_f32_e32 v16, v16, v27
	s_waitcnt lgkmcnt(2)
	v_add_f32_e32 v17, v17, v28
	ds_bpermute_b32 v26, v49, v20
	ds_bpermute_b32 v27, v49, v21
	ds_bpermute_b32 v28, v49, v22
	s_waitcnt lgkmcnt(4)
	v_add_f32_e32 v18, v18, v24
	s_waitcnt lgkmcnt(3)
	v_add_f32_e32 v19, v19, v25
	ds_bpermute_b32 v24, v49, v23
	ds_bpermute_b32 v25, v49, v16
	s_waitcnt lgkmcnt(4)
	v_add_f32_e32 v20, v20, v26
	s_waitcnt lgkmcnt(3)
	v_add_f32_e32 v21, v21, v27
	s_waitcnt lgkmcnt(2)
	v_add_f32_e32 v22, v22, v28
	ds_bpermute_b32 v26, v52, v17
	ds_bpermute_b32 v27, v52, v18
	ds_bpermute_b32 v28, v52, v19
	s_waitcnt lgkmcnt(4)
	v_add_f32_e32 v23, v23, v24
	s_waitcnt lgkmcnt(3)
	v_add_f32_e32 v25, v16, v25
	s_waitcnt lgkmcnt(2)
	v_add_f32_e32 v16, v17, v26
	s_waitcnt lgkmcnt(1)
	v_add_f32_e32 v17, v18, v27
	s_waitcnt lgkmcnt(0)
	v_add_f32_e32 v18, v19, v28
	ds_bpermute_b32 v19, v52, v20
	ds_bpermute_b32 v24, v52, v21
	ds_bpermute_b32 v26, v52, v22
	ds_bpermute_b32 v27, v52, v23
	ds_bpermute_b32 v28, v52, v25
	s_waitcnt lgkmcnt(4)
	v_add_f32_e32 v19, v20, v19
	s_waitcnt lgkmcnt(3)
	v_add_f32_e32 v20, v21, v24
	s_waitcnt lgkmcnt(2)
	v_add_f32_e32 v22, v22, v26
	s_waitcnt lgkmcnt(1)
	v_add_f32_e32 v24, v23, v27
	s_waitcnt lgkmcnt(0)
	v_add_f32_e32 v26, v25, v28
	ds_bpermute_b32 v21, v53, v16
	ds_bpermute_b32 v23, v53, v17
	ds_bpermute_b32 v25, v53, v18
	ds_bpermute_b32 v27, v53, v19
	ds_bpermute_b32 v28, v53, v20
	ds_bpermute_b32 v29, v53, v22
	ds_bpermute_b32 v30, v53, v24
	ds_bpermute_b32 v31, v53, v26
	s_and_b64 s[4:5], s[38:39], s[40:41]
	s_and_saveexec_b64 s[0:1], s[4:5]
	s_cbranch_execz .LBB0_647
	s_waitcnt lgkmcnt(6)
	v_add_f32_e32 v17, v17, v23
	v_add_f32_e32 v16, v16, v21
	s_waitcnt lgkmcnt(5)
	v_add_f32_e32 v18, v18, v25
	v_cndmask_b32_e64 v16, v16, v17, s[42:43]
	s_waitcnt lgkmcnt(4)
	v_add_f32_e32 v19, v19, v27
	v_cndmask_b32_e64 v16, v16, v18, s[44:45]
	s_waitcnt lgkmcnt(3)
	v_add_f32_e32 v20, v20, v28
	v_cndmask_b32_e64 v16, v16, v19, s[46:47]
	s_waitcnt lgkmcnt(2)
	v_add_f32_e32 v22, v22, v29
	v_cndmask_b32_e64 v16, v16, v20, s[48:49]
	s_waitcnt lgkmcnt(1)
	v_add_f32_e32 v24, v24, v30
	v_cndmask_b32_e64 v16, v16, v22, s[50:51]
	s_waitcnt lgkmcnt(0)
	v_add_f32_e32 v26, v26, v31
	v_cndmask_b32_e64 v16, v16, v24, s[52:53]
	v_cndmask_b32_e64 v18, v16, v26, s[54:55]
	v_lshlrev_b64 v[16:17], 5, v[98:99]
	v_lshl_add_u64 v[16:17], v[60:61], 0, v[16:17]
	global_store_dword v[16:17], v18, off
.LBB0_647:
	s_or_b64 exec, exec, s[0:1]
	v_lshlrev_b32_e32 v24, 16, v12
	s_waitcnt lgkmcnt(5)
	v_and_b32_e32 v25, 0xffff0000, v12
	v_lshlrev_b32_e32 v12, 2, v104
	v_and_b32_e32 v194, -16, v12
	ds_read_b128 v[136:139], v194
	ds_read_b128 v[140:143], v194 offset:16
	ds_read_b128 v[144:147], v194 offset:8192
	ds_read_b128 v[148:151], v194 offset:8208
	ds_read_b128 v[152:155], v194 offset:16384
	ds_read_b128 v[156:159], v194 offset:16400
	ds_read_b128 v[160:163], v194 offset:24576
	ds_read_b128 v[164:167], v194 offset:24592
	ds_read_b128 v[196:199], v194 offset:32768
	ds_read_b128 v[200:203], v194 offset:32784
	v_lshlrev_b32_e32 v27, 16, v14
	v_and_b32_e32 v28, 0xffff0000, v14
	s_waitcnt lgkmcnt(9)
	v_mul_f32_e32 v31, v137, v25
	v_lshlrev_b32_e32 v26, 16, v13
	v_fmac_f32_e32 v31, v136, v24
	v_fmac_f32_e32 v31, v138, v26
	v_and_b32_e32 v13, 0xffff0000, v13
	v_lshlrev_b32_e32 v29, 16, v15
	v_and_b32_e32 v30, 0xffff0000, v15
	ds_read_b128 v[204:207], v194 offset:40960
	ds_read_b128 v[208:211], v194 offset:40976
	v_fmac_f32_e32 v31, v139, v13
	s_waitcnt lgkmcnt(10)
	v_fmac_f32_e32 v31, v140, v27
	v_fmac_f32_e32 v31, v141, v28
	v_fmac_f32_e32 v31, v142, v29
	v_fmac_f32_e32 v31, v143, v30
	s_waitcnt lgkmcnt(9)
	v_mul_f32_e32 v23, v145, v25
	v_fmac_f32_e32 v23, v144, v24
	v_fmac_f32_e32 v23, v146, v26
	v_fmac_f32_e32 v23, v147, v13
	s_waitcnt lgkmcnt(8)
	v_fmac_f32_e32 v23, v148, v27
	ds_read_b128 v[136:139], v194 offset:49152
	ds_read_b128 v[140:143], v194 offset:49168
	v_fmac_f32_e32 v23, v149, v28
	v_fmac_f32_e32 v23, v150, v29
	v_fmac_f32_e32 v23, v151, v30
	v_add_f32_e32 v22, 0, v31
	s_waitcnt lgkmcnt(9)
	v_mul_f32_e32 v31, v153, v25
	v_fmac_f32_e32 v31, v152, v24
	v_fmac_f32_e32 v31, v154, v26
	v_fmac_f32_e32 v31, v155, v13
	s_waitcnt lgkmcnt(8)
	v_fmac_f32_e32 v31, v156, v27
	ds_read_b128 v[144:147], v194 offset:57344
	ds_read_b128 v[148:151], v194 offset:57360
	v_fmac_f32_e32 v31, v157, v28
	v_fmac_f32_e32 v31, v158, v29
	v_fmac_f32_e32 v31, v159, v30
	s_waitcnt lgkmcnt(9)
	v_mul_f32_e32 v32, v161, v25
	v_fmac_f32_e32 v32, v160, v24
	v_fmac_f32_e32 v32, v162, v26
	v_fmac_f32_e32 v32, v163, v13
	s_waitcnt lgkmcnt(8)
	v_fmac_f32_e32 v32, v164, v27
	ds_read_b128 v[152:155], v194 offset:2048
	ds_read_b128 v[156:159], v194 offset:2064
	v_fmac_f32_e32 v32, v165, v28
	v_fmac_f32_e32 v32, v166, v29
	v_fmac_f32_e32 v32, v167, v30
	s_waitcnt lgkmcnt(9)
	v_mul_f32_e32 v33, v197, v25
	v_fmac_f32_e32 v33, v196, v24
	v_fmac_f32_e32 v33, v198, v26
	v_fmac_f32_e32 v33, v199, v13
	s_waitcnt lgkmcnt(8)
	v_fmac_f32_e32 v33, v200, v27
	ds_read_b128 v[160:163], v194 offset:10240
	ds_read_b128 v[164:167], v194 offset:10256
	v_fmac_f32_e32 v33, v201, v28
	v_fmac_f32_e32 v33, v202, v29
	v_fmac_f32_e32 v33, v203, v30
	s_waitcnt lgkmcnt(9)
	v_mul_f32_e32 v34, v205, v25
	v_fmac_f32_e32 v34, v204, v24
	v_fmac_f32_e32 v34, v206, v26
	v_fmac_f32_e32 v34, v207, v13
	s_waitcnt lgkmcnt(8)
	v_fmac_f32_e32 v34, v208, v27
	ds_read_b128 v[196:199], v194 offset:18432
	ds_read_b128 v[200:203], v194 offset:18448
	v_fmac_f32_e32 v34, v209, v28
	v_fmac_f32_e32 v34, v210, v29
	v_fmac_f32_e32 v34, v211, v30
	s_waitcnt lgkmcnt(9)
	v_mul_f32_e32 v35, v137, v25
	v_fmac_f32_e32 v35, v136, v24
	v_fmac_f32_e32 v35, v138, v26
	v_fmac_f32_e32 v35, v139, v13
	s_waitcnt lgkmcnt(8)
	v_fmac_f32_e32 v35, v140, v27
	ds_read_b128 v[204:207], v194 offset:26624
	ds_read_b128 v[208:211], v194 offset:26640
	v_fmac_f32_e32 v35, v141, v28
	v_fmac_f32_e32 v35, v142, v29
	v_fmac_f32_e32 v35, v143, v30
	s_waitcnt lgkmcnt(9)
	v_mul_f32_e32 v15, v145, v25
	v_fmac_f32_e32 v15, v144, v24
	v_fmac_f32_e32 v15, v146, v26
	v_fmac_f32_e32 v15, v147, v13
	s_waitcnt lgkmcnt(8)
	v_fmac_f32_e32 v15, v148, v27
	v_fmac_f32_e32 v15, v149, v28
	v_lshlrev_b32_e32 v18, 16, v8
	v_and_b32_e32 v19, 0xffff0000, v8
	v_fmac_f32_e32 v15, v150, v29
	v_fmac_f32_e32 v15, v151, v30
	v_add_f32_e32 v13, 0, v15
	ds_read_b128 v[136:139], v194 offset:34816
	ds_read_b128 v[140:143], v194 offset:34832
	v_lshlrev_b32_e32 v20, 16, v9
	v_and_b32_e32 v21, 0xffff0000, v9
	v_lshlrev_b32_e32 v24, 16, v10
	v_and_b32_e32 v25, 0xffff0000, v10
	v_lshlrev_b32_e32 v26, 16, v11
	v_and_b32_e32 v27, 0xffff0000, v11
	s_waitcnt lgkmcnt(9)
	v_mul_f32_e32 v28, v153, v19
	v_fmac_f32_e32 v28, v152, v18
	v_fmac_f32_e32 v28, v154, v20
	v_fmac_f32_e32 v28, v155, v21
	s_waitcnt lgkmcnt(8)
	v_fmac_f32_e32 v28, v156, v24
	ds_read_b128 v[144:147], v194 offset:43008
	ds_read_b128 v[148:151], v194 offset:43024
	v_fmac_f32_e32 v28, v157, v25
	v_fmac_f32_e32 v28, v158, v26
	v_fmac_f32_e32 v28, v159, v27
	v_add_f32_e32 v22, v22, v28
	s_waitcnt lgkmcnt(9)
	v_mul_f32_e32 v28, v161, v19
	v_fmac_f32_e32 v28, v160, v18
	v_fmac_f32_e32 v28, v162, v20
	v_fmac_f32_e32 v28, v163, v21
	s_waitcnt lgkmcnt(8)
	v_fmac_f32_e32 v28, v164, v24
	ds_read_b128 v[152:155], v194 offset:51200
	ds_read_b128 v[156:159], v194 offset:51216
	v_fmac_f32_e32 v28, v165, v25
	v_fmac_f32_e32 v28, v166, v26
	v_add_f32_e32 v23, 0, v23
	v_fmac_f32_e32 v28, v167, v27
	v_add_f32_e32 v23, v23, v28
	s_waitcnt lgkmcnt(9)
	v_mul_f32_e32 v28, v197, v19
	v_fmac_f32_e32 v28, v196, v18
	v_fmac_f32_e32 v28, v198, v20
	v_fmac_f32_e32 v28, v199, v21
	s_waitcnt lgkmcnt(8)
	v_fmac_f32_e32 v28, v200, v24
	ds_read_b128 v[160:163], v194 offset:59392
	ds_read_b128 v[164:167], v194 offset:59408
	v_fmac_f32_e32 v28, v201, v25
	v_fmac_f32_e32 v28, v202, v26
	v_fmac_f32_e32 v28, v203, v27
	s_waitcnt lgkmcnt(9)
	v_mul_f32_e32 v29, v205, v19
	v_fmac_f32_e32 v29, v204, v18
	v_fmac_f32_e32 v29, v206, v20
	v_fmac_f32_e32 v29, v207, v21
	s_waitcnt lgkmcnt(8)
	v_fmac_f32_e32 v29, v208, v24
	ds_read_b128 v[196:199], v194 offset:4096
	ds_read_b128 v[200:203], v194 offset:4112
	v_fmac_f32_e32 v29, v209, v25
	v_fmac_f32_e32 v29, v210, v26
	v_fmac_f32_e32 v29, v211, v27
	s_waitcnt lgkmcnt(9)
	v_mul_f32_e32 v30, v137, v19
	v_fmac_f32_e32 v30, v136, v18
	v_fmac_f32_e32 v30, v138, v20
	v_fmac_f32_e32 v30, v139, v21
	s_waitcnt lgkmcnt(8)
	v_fmac_f32_e32 v30, v140, v24
	ds_read_b128 v[204:207], v194 offset:12288
	ds_read_b128 v[208:211], v194 offset:12304
	v_fmac_f32_e32 v30, v141, v25
	v_fmac_f32_e32 v30, v142, v26
	v_add_f32_e32 v31, 0, v31
	v_fmac_f32_e32 v30, v143, v27
	v_add_f32_e32 v28, v31, v28
	s_waitcnt lgkmcnt(9)
	v_mul_f32_e32 v31, v145, v19
	v_fmac_f32_e32 v31, v144, v18
	v_fmac_f32_e32 v31, v146, v20
	v_fmac_f32_e32 v31, v147, v21
	s_waitcnt lgkmcnt(8)
	v_fmac_f32_e32 v31, v148, v24
	ds_read_b128 v[136:139], v194 offset:20480
	ds_read_b128 v[140:143], v194 offset:20496
	v_fmac_f32_e32 v31, v149, v25
	v_fmac_f32_e32 v31, v150, v26
	v_add_f32_e32 v32, 0, v32
	v_fmac_f32_e32 v31, v151, v27
	v_add_f32_e32 v29, v32, v29
	s_waitcnt lgkmcnt(9)
	v_mul_f32_e32 v32, v153, v19
	v_fmac_f32_e32 v32, v152, v18
	v_fmac_f32_e32 v32, v154, v20
	v_fmac_f32_e32 v32, v155, v21
	s_waitcnt lgkmcnt(8)
	v_fmac_f32_e32 v32, v156, v24
	ds_read_b128 v[144:147], v194 offset:28672
	ds_read_b128 v[148:151], v194 offset:28688
	v_fmac_f32_e32 v32, v157, v25
	v_fmac_f32_e32 v32, v158, v26
	v_fmac_f32_e32 v32, v159, v27
	s_waitcnt lgkmcnt(9)
	v_mul_f32_e32 v15, v161, v19
	v_fmac_f32_e32 v15, v160, v18
	v_fmac_f32_e32 v15, v162, v20
	v_fmac_f32_e32 v15, v163, v21
	s_waitcnt lgkmcnt(8)
	v_fmac_f32_e32 v15, v164, v24
	v_fmac_f32_e32 v15, v165, v25
	v_fmac_f32_e32 v15, v166, v26
	v_fmac_f32_e32 v15, v167, v27
	v_add_f32_e32 v13, v13, v15
	v_lshlrev_b32_e32 v14, 16, v4
	v_and_b32_e32 v15, 0xffff0000, v4
	ds_read_b128 v[152:155], v194 offset:36864
	ds_read_b128 v[156:159], v194 offset:36880
	v_lshlrev_b32_e32 v16, 16, v5
	v_and_b32_e32 v17, 0xffff0000, v5
	v_lshlrev_b32_e32 v18, 16, v6
	v_and_b32_e32 v19, 0xffff0000, v6
	v_lshlrev_b32_e32 v20, 16, v7
	v_and_b32_e32 v21, 0xffff0000, v7
	s_waitcnt lgkmcnt(9)
	v_mul_f32_e32 v24, v197, v15
	v_fmac_f32_e32 v24, v196, v14
	v_fmac_f32_e32 v24, v198, v16
	v_fmac_f32_e32 v24, v199, v17
	s_waitcnt lgkmcnt(8)
	v_fmac_f32_e32 v24, v200, v18
	ds_read_b128 v[160:163], v194 offset:45056
	ds_read_b128 v[164:167], v194 offset:45072
	v_fmac_f32_e32 v24, v201, v19
	v_fmac_f32_e32 v24, v202, v20
	v_fmac_f32_e32 v24, v203, v21
	v_add_f32_e32 v22, v22, v24
	s_waitcnt lgkmcnt(9)
	v_mul_f32_e32 v24, v205, v15
	v_fmac_f32_e32 v24, v204, v14
	v_fmac_f32_e32 v24, v206, v16
	v_fmac_f32_e32 v24, v207, v17
	s_waitcnt lgkmcnt(8)
	v_fmac_f32_e32 v24, v208, v18
	ds_read_b128 v[196:199], v194 offset:53248
	ds_read_b128 v[200:203], v194 offset:53264
	v_fmac_f32_e32 v24, v209, v19
	v_fmac_f32_e32 v24, v210, v20
	v_fmac_f32_e32 v24, v211, v21
	v_add_f32_e32 v23, v23, v24
	s_waitcnt lgkmcnt(9)
	v_mul_f32_e32 v24, v137, v15
	v_fmac_f32_e32 v24, v136, v14
	v_fmac_f32_e32 v24, v138, v16
	v_fmac_f32_e32 v24, v139, v17
	s_waitcnt lgkmcnt(8)
	v_fmac_f32_e32 v24, v140, v18
	ds_read_b128 v[204:207], v194 offset:61440
	ds_read_b128 v[208:211], v194 offset:61456
	v_fmac_f32_e32 v24, v141, v19
	v_fmac_f32_e32 v24, v142, v20
	v_fmac_f32_e32 v24, v143, v21
	s_waitcnt lgkmcnt(9)
	v_mul_f32_e32 v25, v145, v15
	v_fmac_f32_e32 v25, v144, v14
	v_fmac_f32_e32 v25, v146, v16
	v_fmac_f32_e32 v25, v147, v17
	s_waitcnt lgkmcnt(8)
	v_fmac_f32_e32 v25, v148, v18
	ds_read_b128 v[136:139], v194 offset:6144
	ds_read_b128 v[140:143], v194 offset:6160
	v_fmac_f32_e32 v25, v149, v19
	v_fmac_f32_e32 v25, v150, v20
	v_fmac_f32_e32 v25, v151, v21
	s_waitcnt lgkmcnt(9)
	v_mul_f32_e32 v26, v153, v15
	v_fmac_f32_e32 v26, v152, v14
	v_fmac_f32_e32 v26, v154, v16
	v_fmac_f32_e32 v26, v155, v17
	s_waitcnt lgkmcnt(8)
	v_fmac_f32_e32 v26, v156, v18
	ds_read_b128 v[144:147], v194 offset:14336
	ds_read_b128 v[148:151], v194 offset:14352
	v_fmac_f32_e32 v26, v157, v19
	v_fmac_f32_e32 v26, v158, v20
	v_fmac_f32_e32 v26, v159, v21
	s_waitcnt lgkmcnt(9)
	v_mul_f32_e32 v27, v161, v15
	v_fmac_f32_e32 v27, v160, v14
	v_fmac_f32_e32 v27, v162, v16
	v_fmac_f32_e32 v27, v163, v17
	s_waitcnt lgkmcnt(8)
	v_fmac_f32_e32 v27, v164, v18
	ds_read_b128 v[152:155], v194 offset:22528
	ds_read_b128 v[156:159], v194 offset:22544
	v_fmac_f32_e32 v27, v165, v19
	v_fmac_f32_e32 v27, v166, v20
	v_fmac_f32_e32 v27, v167, v21
	v_add_f32_e32 v24, v28, v24
	s_waitcnt lgkmcnt(9)
	v_mul_f32_e32 v28, v197, v15
	v_fmac_f32_e32 v28, v196, v14
	v_fmac_f32_e32 v28, v198, v16
	v_fmac_f32_e32 v28, v199, v17
	s_waitcnt lgkmcnt(8)
	v_fmac_f32_e32 v28, v200, v18
	ds_read_b128 v[160:163], v194 offset:30720
	ds_read_b128 v[164:167], v194 offset:30736
	v_fmac_f32_e32 v28, v201, v19
	v_fmac_f32_e32 v28, v202, v20
	v_fmac_f32_e32 v28, v203, v21
	s_waitcnt lgkmcnt(9)
	v_mul_f32_e32 v9, v205, v15
	v_fmac_f32_e32 v9, v204, v14
	v_fmac_f32_e32 v9, v206, v16
	v_fmac_f32_e32 v9, v207, v17
	s_waitcnt lgkmcnt(8)
	v_fmac_f32_e32 v9, v208, v18
	v_fmac_f32_e32 v9, v209, v19
	v_fmac_f32_e32 v9, v210, v20
	v_fmac_f32_e32 v9, v211, v21
	v_add_f32_e32 v8, v13, v9
	v_lshlrev_b32_e32 v9, 16, v0
	v_and_b32_e32 v10, 0xffff0000, v0
	ds_read_b128 v[196:199], v194 offset:38912
	ds_read_b128 v[200:203], v194 offset:38928
	v_lshlrev_b32_e32 v11, 16, v1
	v_and_b32_e32 v13, 0xffff0000, v1
	v_lshlrev_b32_e32 v14, 16, v2
	v_and_b32_e32 v15, 0xffff0000, v2
	v_lshlrev_b32_e32 v16, 16, v3
	v_and_b32_e32 v17, 0xffff0000, v3
	s_waitcnt lgkmcnt(9)
	v_mul_f32_e32 v18, v137, v10
	v_fmac_f32_e32 v18, v136, v9
	v_fmac_f32_e32 v18, v138, v11
	v_fmac_f32_e32 v18, v139, v13
	s_waitcnt lgkmcnt(8)
	v_fmac_f32_e32 v18, v140, v14
	ds_read_b128 v[204:207], v194 offset:47104
	ds_read_b128 v[208:211], v194 offset:47120
	v_fmac_f32_e32 v18, v141, v15
	v_fmac_f32_e32 v18, v142, v16
	v_fmac_f32_e32 v18, v143, v17
	s_waitcnt lgkmcnt(9)
	v_mul_f32_e32 v19, v145, v10
	v_fmac_f32_e32 v19, v144, v9
	v_fmac_f32_e32 v19, v146, v11
	v_fmac_f32_e32 v19, v147, v13
	s_waitcnt lgkmcnt(8)
	v_fmac_f32_e32 v19, v148, v14
	ds_read_b128 v[136:139], v194 offset:55296
	ds_read_b128 v[140:143], v194 offset:55312
	v_fmac_f32_e32 v19, v149, v15
	v_fmac_f32_e32 v19, v150, v16
	v_fmac_f32_e32 v19, v151, v17
	s_waitcnt lgkmcnt(9)
	v_mul_f32_e32 v20, v153, v10
	v_fmac_f32_e32 v20, v152, v9
	v_fmac_f32_e32 v20, v154, v11
	v_fmac_f32_e32 v20, v155, v13
	s_waitcnt lgkmcnt(8)
	v_fmac_f32_e32 v20, v156, v14
	ds_read_b128 v[144:147], v194 offset:63488
	ds_read_b128 v[148:151], v194 offset:63504
	v_fmac_f32_e32 v20, v157, v15
	v_fmac_f32_e32 v20, v158, v16
	v_fmac_f32_e32 v20, v159, v17
	s_waitcnt lgkmcnt(9)
	v_mul_f32_e32 v21, v161, v10
	v_fmac_f32_e32 v21, v160, v9
	v_fmac_f32_e32 v21, v162, v11
	v_fmac_f32_e32 v21, v163, v13
	s_waitcnt lgkmcnt(8)
	v_fmac_f32_e32 v21, v164, v14
	v_fmac_f32_e32 v21, v165, v15
	v_fmac_f32_e32 v21, v166, v16
	v_fmac_f32_e32 v21, v167, v17
	v_add_f32_e32 v18, v22, v18
	s_waitcnt lgkmcnt(7)
	v_mul_f32_e32 v22, v197, v10
	v_fmac_f32_e32 v22, v196, v9
	v_fmac_f32_e32 v22, v198, v11
	v_fmac_f32_e32 v22, v199, v13
	s_waitcnt lgkmcnt(6)
	v_fmac_f32_e32 v22, v200, v14
	v_fmac_f32_e32 v22, v201, v15
	v_fmac_f32_e32 v22, v202, v16
	v_fmac_f32_e32 v22, v203, v17
	v_add_f32_e32 v19, v23, v19
	s_waitcnt lgkmcnt(5)
	v_mul_f32_e32 v23, v205, v10
	v_fmac_f32_e32 v23, v204, v9
	v_fmac_f32_e32 v23, v206, v11
	v_fmac_f32_e32 v23, v207, v13
	s_waitcnt lgkmcnt(4)
	v_fmac_f32_e32 v23, v208, v14
	v_fmac_f32_e32 v23, v209, v15
	v_fmac_f32_e32 v23, v210, v16
	v_fmac_f32_e32 v23, v211, v17
	v_add_f32_e32 v20, v24, v20
	s_waitcnt lgkmcnt(3)
	v_mul_f32_e32 v24, v137, v10
	v_fmac_f32_e32 v24, v136, v9
	v_fmac_f32_e32 v24, v138, v11
	v_fmac_f32_e32 v24, v139, v13
	s_waitcnt lgkmcnt(2)
	v_fmac_f32_e32 v24, v140, v14
	v_fmac_f32_e32 v24, v141, v15
	v_fmac_f32_e32 v24, v142, v16
	v_fmac_f32_e32 v24, v143, v17
	s_waitcnt lgkmcnt(1)
	v_mul_f32_e32 v5, v145, v10
	v_fmac_f32_e32 v5, v144, v9
	v_fmac_f32_e32 v5, v146, v11
	v_fmac_f32_e32 v5, v147, v13
	s_waitcnt lgkmcnt(0)
	v_fmac_f32_e32 v5, v148, v14
	v_fmac_f32_e32 v5, v149, v15
	ds_bpermute_b32 v1, v50, v18
	v_fmac_f32_e32 v5, v150, v16
	ds_bpermute_b32 v2, v50, v19
	v_add_f32_e32 v33, 0, v33
	v_add_f32_e32 v34, 0, v34
	v_add_f32_e32 v35, 0, v35
	v_add_f32_e32 v30, v33, v30
	v_add_f32_e32 v31, v34, v31
	v_add_f32_e32 v32, v35, v32
	v_add_f32_e32 v25, v29, v25
	v_add_f32_e32 v26, v30, v26
	v_add_f32_e32 v27, v31, v27
	v_add_f32_e32 v28, v32, v28
	v_add_f32_e32 v21, v25, v21
	v_fmac_f32_e32 v5, v151, v17
	v_add_f32_e32 v22, v26, v22
	v_add_f32_e32 v23, v27, v23
	v_add_f32_e32 v12, v28, v24
	v_add_f32_e32 v0, v8, v5
	ds_bpermute_b32 v3, v50, v20
	ds_bpermute_b32 v4, v50, v21
	s_waitcnt lgkmcnt(3)
	v_add_f32_e32 v1, v18, v1
	ds_bpermute_b32 v5, v50, v22
	s_waitcnt lgkmcnt(3)
	v_add_f32_e32 v2, v19, v2
	ds_bpermute_b32 v6, v50, v23
	ds_bpermute_b32 v7, v50, v12
	ds_bpermute_b32 v8, v50, v0
	ds_bpermute_b32 v9, v48, v1
	ds_bpermute_b32 v10, v48, v2
	s_waitcnt lgkmcnt(7)
	v_add_f32_e32 v3, v20, v3
	s_waitcnt lgkmcnt(6)
	v_add_f32_e32 v4, v21, v4
	s_waitcnt lgkmcnt(5)
	v_add_f32_e32 v5, v22, v5
	s_waitcnt lgkmcnt(4)
	v_add_f32_e32 v6, v23, v6
	s_waitcnt lgkmcnt(3)
	v_add_f32_e32 v7, v12, v7
	s_waitcnt lgkmcnt(2)
	v_add_f32_e32 v0, v0, v8
	s_waitcnt lgkmcnt(1)
	v_add_f32_e32 v1, v1, v9
	ds_bpermute_b32 v8, v48, v3
	ds_bpermute_b32 v9, v48, v4
	s_waitcnt lgkmcnt(2)
	v_add_f32_e32 v2, v2, v10
	ds_bpermute_b32 v10, v48, v5
	ds_bpermute_b32 v11, v48, v6
	ds_bpermute_b32 v12, v48, v7
	s_waitcnt lgkmcnt(4)
	v_add_f32_e32 v3, v3, v8
	s_waitcnt lgkmcnt(3)
	v_add_f32_e32 v4, v4, v9
	ds_bpermute_b32 v8, v48, v0
	ds_bpermute_b32 v9, v51, v1
	s_waitcnt lgkmcnt(4)
	v_add_f32_e32 v5, v5, v10
	s_waitcnt lgkmcnt(3)
	v_add_f32_e32 v6, v6, v11
	s_waitcnt lgkmcnt(2)
	v_add_f32_e32 v7, v7, v12
	ds_bpermute_b32 v10, v51, v2
	ds_bpermute_b32 v11, v51, v3
	ds_bpermute_b32 v12, v51, v4
	s_waitcnt lgkmcnt(4)
	v_add_f32_e32 v0, v0, v8
	s_waitcnt lgkmcnt(3)
	v_add_f32_e32 v1, v1, v9
	ds_bpermute_b32 v8, v51, v5
	ds_bpermute_b32 v9, v51, v6
	s_waitcnt lgkmcnt(4)
	v_add_f32_e32 v2, v2, v10
	s_waitcnt lgkmcnt(3)
	v_add_f32_e32 v3, v3, v11
	s_waitcnt lgkmcnt(2)
	v_add_f32_e32 v4, v4, v12
	ds_bpermute_b32 v10, v51, v7
	ds_bpermute_b32 v11, v51, v0
	ds_bpermute_b32 v12, v49, v1
	s_waitcnt lgkmcnt(4)
	v_add_f32_e32 v5, v5, v8
	s_waitcnt lgkmcnt(3)
	v_add_f32_e32 v6, v6, v9
	ds_bpermute_b32 v8, v49, v2
	ds_bpermute_b32 v9, v49, v3
	s_waitcnt lgkmcnt(4)
	v_add_f32_e32 v7, v7, v10
	s_waitcnt lgkmcnt(3)
	v_add_f32_e32 v0, v0, v11
	s_waitcnt lgkmcnt(2)
	v_add_f32_e32 v1, v1, v12
	ds_bpermute_b32 v10, v49, v4
	ds_bpermute_b32 v11, v49, v5
	ds_bpermute_b32 v12, v49, v6
	s_waitcnt lgkmcnt(4)
	v_add_f32_e32 v2, v2, v8
	s_waitcnt lgkmcnt(3)
	v_add_f32_e32 v3, v3, v9
	ds_bpermute_b32 v8, v49, v7
	ds_bpermute_b32 v9, v49, v0
	s_waitcnt lgkmcnt(4)
	v_add_f32_e32 v4, v4, v10
	s_waitcnt lgkmcnt(3)
	v_add_f32_e32 v5, v5, v11
	s_waitcnt lgkmcnt(2)
	v_add_f32_e32 v6, v6, v12
	ds_bpermute_b32 v10, v52, v1
	ds_bpermute_b32 v11, v52, v2
	ds_bpermute_b32 v12, v52, v3
	s_waitcnt lgkmcnt(4)
	v_add_f32_e32 v7, v7, v8
	s_waitcnt lgkmcnt(3)
	v_add_f32_e32 v9, v0, v9
	s_waitcnt lgkmcnt(2)
	v_add_f32_e32 v0, v1, v10
	s_waitcnt lgkmcnt(1)
	v_add_f32_e32 v1, v2, v11
	s_waitcnt lgkmcnt(0)
	v_add_f32_e32 v2, v3, v12
	ds_bpermute_b32 v3, v52, v4
	ds_bpermute_b32 v8, v52, v5
	ds_bpermute_b32 v10, v52, v6
	ds_bpermute_b32 v11, v52, v7
	ds_bpermute_b32 v12, v52, v9
	s_waitcnt lgkmcnt(4)
	v_add_f32_e32 v3, v4, v3
	s_waitcnt lgkmcnt(3)
	v_add_f32_e32 v4, v5, v8
	s_waitcnt lgkmcnt(2)
	v_add_f32_e32 v6, v6, v10
	s_waitcnt lgkmcnt(1)
	v_add_f32_e32 v8, v7, v11
	s_waitcnt lgkmcnt(0)
	v_add_f32_e32 v10, v9, v12
	ds_bpermute_b32 v5, v53, v0
	ds_bpermute_b32 v7, v53, v1
	ds_bpermute_b32 v9, v53, v2
	ds_bpermute_b32 v11, v53, v3
	ds_bpermute_b32 v12, v53, v4
	ds_bpermute_b32 v13, v53, v6
	ds_bpermute_b32 v14, v53, v8
	ds_bpermute_b32 v15, v53, v10
	s_and_b64 s[4:5], s[38:39], vcc
	s_and_saveexec_b64 s[0:1], s[4:5]
	s_cbranch_execz .LBB0_649
	s_waitcnt lgkmcnt(6)
	v_add_f32_e32 v1, v1, v7
	v_add_f32_e32 v0, v0, v5
	s_waitcnt lgkmcnt(5)
	v_add_f32_e32 v2, v2, v9
	v_cndmask_b32_e64 v0, v0, v1, s[42:43]
	s_waitcnt lgkmcnt(4)
	v_add_f32_e32 v3, v3, v11
	v_cndmask_b32_e64 v0, v0, v2, s[44:45]
	s_waitcnt lgkmcnt(3)
	v_add_f32_e32 v4, v4, v12
	v_cndmask_b32_e64 v0, v0, v3, s[46:47]
	s_waitcnt lgkmcnt(2)
	v_add_f32_e32 v6, v6, v13
	v_cndmask_b32_e64 v0, v0, v4, s[48:49]
	s_waitcnt lgkmcnt(1)
	v_add_f32_e32 v8, v8, v14
	v_cndmask_b32_e64 v0, v0, v6, s[50:51]
	s_waitcnt lgkmcnt(0)
	v_add_f32_e32 v10, v10, v15
	v_cndmask_b32_e64 v0, v0, v8, s[52:53]
	v_cndmask_b32_e64 v2, v0, v10, s[54:55]
	v_lshlrev_b64 v[0:1], 5, v[96:97]
	v_lshl_add_u64 v[0:1], v[60:61], 0, v[0:1]
	global_store_dword v[0:1], v2, off
